# nt (streaming) stores for write-once data: PA outputs, kv_prep outputs (KC/VC/new_k/new_v), final-norm outputs, prologue tables
# baseline (speedup 1.0000x reference)
.Ltr_dec2:
	s_add_u32 s40, s8, s31
	s_addc_u32 s41, s9, 0
	v_mad_u32_u24 v16, v3, s14, v2
	v_add_u32_e32 v17, s14, v16
	v_add_u32_e32 v18, s14, v17
	v_add_u32_e32 v19, s14, v18
	v_add_u32_e32 v20, s14, v19
	v_add_u32_e32 v21, s14, v20
	v_add_u32_e32 v22, s14, v21
	v_add_u32_e32 v23, s14, v22
	v_mad_u32_u24 v28, v4, s15, v5
	v_add_u32_e32 v29, s15, v28
	v_add_u32_e32 v30, s15, v29
	v_add_u32_e32 v31, s15, v30
	global_load_dwordx4 v[128:131], v16, s[16:17] nt
	global_load_dwordx4 v[132:135], v17, s[16:17] nt
	global_load_dwordx4 v[136:139], v18, s[16:17] nt
	global_load_dwordx4 v[140:143], v19, s[16:17] nt
	global_load_dwordx4 v[144:147], v20, s[16:17] nt
	global_load_dwordx4 v[148:151], v21, s[16:17] nt
	global_load_dwordx4 v[152:155], v22, s[16:17] nt
	global_load_dwordx4 v[156:159], v23, s[16:17] nt
	global_load_dwordx4 v[160:163], v16, s[16:17] offset:128 nt
	global_load_dwordx4 v[164:167], v17, s[16:17] offset:128 nt
	global_load_dwordx4 v[168:171], v18, s[16:17] offset:128 nt
	global_load_dwordx4 v[172:175], v19, s[16:17] offset:128 nt
	global_load_dwordx4 v[176:179], v20, s[16:17] offset:128 nt
	global_load_dwordx4 v[180:183], v21, s[16:17] offset:128 nt
	global_load_dwordx4 v[184:187], v22, s[16:17] offset:128 nt
	global_load_dwordx4 v[188:191], v23, s[16:17] offset:128 nt
	s_waitcnt vmcnt(16)
	v_cvt_pk_bf16_f32 v192, v64, v68
	v_cvt_pk_bf16_f32 v193, v72, v76
	v_cvt_pk_bf16_f32 v194, v80, v84
	v_cvt_pk_bf16_f32 v195, v88, v92
	v_cvt_pk_bf16_f32 v196, v65, v69
	v_cvt_pk_bf16_f32 v197, v73, v77
	v_cvt_pk_bf16_f32 v198, v81, v85
	v_cvt_pk_bf16_f32 v199, v89, v93
	v_cvt_pk_bf16_f32 v200, v66, v70
	v_cvt_pk_bf16_f32 v201, v74, v78
	v_cvt_pk_bf16_f32 v202, v82, v86
	v_cvt_pk_bf16_f32 v203, v90, v94
	v_cvt_pk_bf16_f32 v204, v67, v71
	v_cvt_pk_bf16_f32 v205, v75, v79
	v_cvt_pk_bf16_f32 v206, v83, v87
	v_cvt_pk_bf16_f32 v207, v91, v95
	global_store_dwordx4 v24, v[192:195], s[18:19] nt
	global_store_dwordx4 v25, v[196:199], s[18:19] nt
	global_store_dwordx4 v26, v[200:203], s[18:19] nt
	global_store_dwordx4 v27, v[204:207], s[18:19] nt
	v_cvt_pk_bf16_f32 v48, v96, v100
	v_cvt_pk_bf16_f32 v49, v104, v108
	v_cvt_pk_bf16_f32 v50, v112, v116
	v_cvt_pk_bf16_f32 v51, v120, v124
	v_cvt_pk_bf16_f32 v52, v97, v101
	v_cvt_pk_bf16_f32 v53, v105, v109
	v_cvt_pk_bf16_f32 v54, v113, v117
	v_cvt_pk_bf16_f32 v55, v121, v125
	v_cvt_pk_bf16_f32 v56, v98, v102
	v_cvt_pk_bf16_f32 v57, v106, v110
	v_cvt_pk_bf16_f32 v58, v114, v118
	v_cvt_pk_bf16_f32 v59, v122, v126
	v_cvt_pk_bf16_f32 v60, v99, v103
	v_cvt_pk_bf16_f32 v61, v107, v111
	v_cvt_pk_bf16_f32 v62, v115, v119
	v_cvt_pk_bf16_f32 v63, v123, v127
	s_add_u32 s10, s18, s34
	s_addc_u32 s11, s19, 0
	global_store_dwordx4 v24, v[48:51], s[10:11] nt
	global_store_dwordx4 v25, v[52:55], s[10:11] nt
	global_store_dwordx4 v26, v[56:59], s[10:11] nt
	global_store_dwordx4 v27, v[60:63], s[10:11] nt
	s_add_u32 s29, s29, s30
	s_cmp_gt_u32 s29, 0xd7ff
	s_cbranch_scc1 .Ltr_lastB
	s_mov_b32 s11, s29
	s_cmp_ge_u32 s11, 0x6c00
	s_cselect_b32 s16, 0x6c00, 0
	s_cselect_b32 s10, 2, 0
	s_sub_u32 s11, s11, s16
	s_cmp_ge_u32 s11, 0x3600
	s_cselect_b32 s16, 0x3600, 0
	s_cselect_b32 s17, 1, 0
	s_sub_u32 s11, s11, s16
	s_add_u32 s10, s10, s17
	s_cmp_lt_u32 s11, 0x2400
	s_cbranch_scc1 .Ltr_in3
	s_cmp_lt_u32 s11, 0x3400
	s_cbranch_scc1 .Ltr_out3
	s_sub_u32 s11, s11, 0x3400
	s_lshr_b32 s16, s11, 5
	s_and_b32 s17, s11, 31
	s_movk_i32 s14, 0x2000
	s_movk_i32 s15, 0x800
	s_mov_b32 s34, 0x10000
	s_lshl_b32 s31, s10, 23
	s_lshl_b32 s11, s16, 19
	s_add_u32 s31, s31, s11
	s_lshl_b32 s11, s17, 8
	s_add_u32 s31, s31, s11
	s_add_u32 s31, s6, s31
	s_addc_u32 s11, s7, 0
	s_bfe_u32 s14, s17, 0x30001
	s_lshl_b32 s14, s14, 8
	s_lshr_b32 s15, s17, 4
	s_lshl_b32 s15, s15, 7
	s_add_u32 s14, s14, s15
	s_and_b32 s15, s17, 1
	s_lshl_b32 s15, s15, 6
	s_add_u32 s14, s14, s15
	s_lshl_b32 s14, s14, 11
	s_lshl_b32 s15, s16, 7
	s_add_u32 s14, s14, s15
	s_lshl_b32 s15, s10, 22
	s_add_u32 s14, s14, s15
	s_add_u32 s17, s14, 0xae00000
	s_mov_b32 s16, s31
	s_mov_b32 s31, s17
	s_mov_b32 s17, s11
	s_movk_i32 s14, 0x2000
	s_movk_i32 s15, 0x800
	s_branch .Ltr_dec3

.Ltr_dec3:
	s_add_u32 s18, s8, s31
	s_addc_u32 s19, s9, 0
	v_mad_u32_u24 v16, v3, s14, v2
	v_add_u32_e32 v17, s14, v16
	v_add_u32_e32 v18, s14, v17
	v_add_u32_e32 v19, s14, v18
	v_add_u32_e32 v20, s14, v19
	v_add_u32_e32 v21, s14, v20
	v_add_u32_e32 v22, s14, v21
	v_add_u32_e32 v23, s14, v22
	v_mad_u32_u24 v24, v4, s15, v5
	v_add_u32_e32 v25, s15, v24
	v_add_u32_e32 v26, s15, v25
	v_add_u32_e32 v27, s15, v26
	global_load_dwordx4 v[64:67], v16, s[16:17] nt
	global_load_dwordx4 v[68:71], v17, s[16:17] nt
	global_load_dwordx4 v[72:75], v18, s[16:17] nt
	global_load_dwordx4 v[76:79], v19, s[16:17] nt
	global_load_dwordx4 v[80:83], v20, s[16:17] nt
	global_load_dwordx4 v[84:87], v21, s[16:17] nt
	global_load_dwordx4 v[88:91], v22, s[16:17] nt
	global_load_dwordx4 v[92:95], v23, s[16:17] nt
	global_load_dwordx4 v[96:99], v16, s[16:17] offset:128 nt
	global_load_dwordx4 v[100:103], v17, s[16:17] offset:128 nt
	global_load_dwordx4 v[104:107], v18, s[16:17] offset:128 nt
	global_load_dwordx4 v[108:111], v19, s[16:17] offset:128 nt
	global_load_dwordx4 v[112:115], v20, s[16:17] offset:128 nt
	global_load_dwordx4 v[116:119], v21, s[16:17] offset:128 nt
	global_load_dwordx4 v[120:123], v22, s[16:17] offset:128 nt
	global_load_dwordx4 v[124:127], v23, s[16:17] offset:128 nt
	s_waitcnt vmcnt(16)
	v_cvt_pk_bf16_f32 v192, v128, v132
	v_cvt_pk_bf16_f32 v193, v136, v140
	v_cvt_pk_bf16_f32 v194, v144, v148
	v_cvt_pk_bf16_f32 v195, v152, v156
	v_cvt_pk_bf16_f32 v196, v129, v133
	v_cvt_pk_bf16_f32 v197, v137, v141
	v_cvt_pk_bf16_f32 v198, v145, v149
	v_cvt_pk_bf16_f32 v199, v153, v157
	v_cvt_pk_bf16_f32 v200, v130, v134
	v_cvt_pk_bf16_f32 v201, v138, v142
	v_cvt_pk_bf16_f32 v202, v146, v150
	v_cvt_pk_bf16_f32 v203, v154, v158
	v_cvt_pk_bf16_f32 v204, v131, v135
	v_cvt_pk_bf16_f32 v205, v139, v143
	v_cvt_pk_bf16_f32 v206, v147, v151
	v_cvt_pk_bf16_f32 v207, v155, v159
	global_store_dwordx4 v28, v[192:195], s[40:41] nt
	global_store_dwordx4 v29, v[196:199], s[40:41] nt
	global_store_dwordx4 v30, v[200:203], s[40:41] nt
	global_store_dwordx4 v31, v[204:207], s[40:41] nt
	v_cvt_pk_bf16_f32 v48, v160, v164
	v_cvt_pk_bf16_f32 v49, v168, v172
	v_cvt_pk_bf16_f32 v50, v176, v180
	v_cvt_pk_bf16_f32 v51, v184, v188
	v_cvt_pk_bf16_f32 v52, v161, v165
	v_cvt_pk_bf16_f32 v53, v169, v173
	v_cvt_pk_bf16_f32 v54, v177, v181
	v_cvt_pk_bf16_f32 v55, v185, v189
	v_cvt_pk_bf16_f32 v56, v162, v166
	v_cvt_pk_bf16_f32 v57, v170, v174
	v_cvt_pk_bf16_f32 v58, v178, v182
	v_cvt_pk_bf16_f32 v59, v186, v190
	v_cvt_pk_bf16_f32 v60, v163, v167
	v_cvt_pk_bf16_f32 v61, v171, v175
	v_cvt_pk_bf16_f32 v62, v179, v183
	v_cvt_pk_bf16_f32 v63, v187, v191
	s_add_u32 s10, s40, s35
	s_addc_u32 s11, s41, 0
	global_store_dwordx4 v28, v[48:51], s[10:11] nt
	global_store_dwordx4 v29, v[52:55], s[10:11] nt
	global_store_dwordx4 v30, v[56:59], s[10:11] nt
	global_store_dwordx4 v31, v[60:63], s[10:11] nt
	s_branch .Ltr_loop
.Ltr_lastA:
	s_waitcnt vmcnt(0)
	v_cvt_pk_bf16_f32 v192, v64, v68
	v_cvt_pk_bf16_f32 v193, v72, v76
	v_cvt_pk_bf16_f32 v194, v80, v84
	v_cvt_pk_bf16_f32 v195, v88, v92
	v_cvt_pk_bf16_f32 v196, v65, v69
	v_cvt_pk_bf16_f32 v197, v73, v77
	v_cvt_pk_bf16_f32 v198, v81, v85
	v_cvt_pk_bf16_f32 v199, v89, v93
	v_cvt_pk_bf16_f32 v200, v66, v70
	v_cvt_pk_bf16_f32 v201, v74, v78
	v_cvt_pk_bf16_f32 v202, v82, v86
	v_cvt_pk_bf16_f32 v203, v90, v94
	v_cvt_pk_bf16_f32 v204, v67, v71
	v_cvt_pk_bf16_f32 v205, v75, v79
	v_cvt_pk_bf16_f32 v206, v83, v87
	v_cvt_pk_bf16_f32 v207, v91, v95
	global_store_dwordx4 v24, v[192:195], s[18:19] nt
	global_store_dwordx4 v25, v[196:199], s[18:19] nt
	global_store_dwordx4 v26, v[200:203], s[18:19] nt
	global_store_dwordx4 v27, v[204:207], s[18:19] nt
	v_cvt_pk_bf16_f32 v48, v96, v100
	v_cvt_pk_bf16_f32 v49, v104, v108
	v_cvt_pk_bf16_f32 v50, v112, v116
	v_cvt_pk_bf16_f32 v51, v120, v124
	v_cvt_pk_bf16_f32 v52, v97, v101
	v_cvt_pk_bf16_f32 v53, v105, v109
	v_cvt_pk_bf16_f32 v54, v113, v117
	v_cvt_pk_bf16_f32 v55, v121, v125
	v_cvt_pk_bf16_f32 v56, v98, v102
	v_cvt_pk_bf16_f32 v57, v106, v110
	v_cvt_pk_bf16_f32 v58, v114, v118
	v_cvt_pk_bf16_f32 v59, v122, v126
	v_cvt_pk_bf16_f32 v60, v99, v103
	v_cvt_pk_bf16_f32 v61, v107, v111
	v_cvt_pk_bf16_f32 v62, v115, v119
	v_cvt_pk_bf16_f32 v63, v123, v127
	s_add_u32 s10, s18, s34
	s_addc_u32 s11, s19, 0
	global_store_dwordx4 v24, v[48:51], s[10:11] nt
	global_store_dwordx4 v25, v[52:55], s[10:11] nt
	global_store_dwordx4 v26, v[56:59], s[10:11] nt
	global_store_dwordx4 v27, v[60:63], s[10:11] nt
	s_branch .LBB0_58
.Ltr_lastB:
	s_waitcnt vmcnt(0)
	v_cvt_pk_bf16_f32 v192, v128, v132
	v_cvt_pk_bf16_f32 v193, v136, v140
	v_cvt_pk_bf16_f32 v194, v144, v148
	v_cvt_pk_bf16_f32 v195, v152, v156
	v_cvt_pk_bf16_f32 v196, v129, v133
	v_cvt_pk_bf16_f32 v197, v137, v141
	v_cvt_pk_bf16_f32 v198, v145, v149
	v_cvt_pk_bf16_f32 v199, v153, v157
	v_cvt_pk_bf16_f32 v200, v130, v134
	v_cvt_pk_bf16_f32 v201, v138, v142
	v_cvt_pk_bf16_f32 v202, v146, v150
	v_cvt_pk_bf16_f32 v203, v154, v158
	v_cvt_pk_bf16_f32 v204, v131, v135
	v_cvt_pk_bf16_f32 v205, v139, v143
	v_cvt_pk_bf16_f32 v206, v147, v151
	v_cvt_pk_bf16_f32 v207, v155, v159
	global_store_dwordx4 v28, v[192:195], s[40:41] nt
	global_store_dwordx4 v29, v[196:199], s[40:41] nt
	global_store_dwordx4 v30, v[200:203], s[40:41] nt
	global_store_dwordx4 v31, v[204:207], s[40:41] nt
	v_cvt_pk_bf16_f32 v48, v160, v164
	v_cvt_pk_bf16_f32 v49, v168, v172
	v_cvt_pk_bf16_f32 v50, v176, v180
	v_cvt_pk_bf16_f32 v51, v184, v188
	v_cvt_pk_bf16_f32 v52, v161, v165
	v_cvt_pk_bf16_f32 v53, v169, v173
	v_cvt_pk_bf16_f32 v54, v177, v181
	v_cvt_pk_bf16_f32 v55, v185, v189
	v_cvt_pk_bf16_f32 v56, v162, v166
	v_cvt_pk_bf16_f32 v57, v170, v174
	v_cvt_pk_bf16_f32 v58, v178, v182
	v_cvt_pk_bf16_f32 v59, v186, v190
	v_cvt_pk_bf16_f32 v60, v163, v167
	v_cvt_pk_bf16_f32 v61, v171, v175
	v_cvt_pk_bf16_f32 v62, v179, v183
	v_cvt_pk_bf16_f32 v63, v187, v191
	s_add_u32 s10, s40, s35
	s_addc_u32 s11, s41, 0
	global_store_dwordx4 v28, v[48:51], s[10:11] nt
	global_store_dwordx4 v29, v[52:55], s[10:11] nt
	global_store_dwordx4 v30, v[56:59], s[10:11] nt
	global_store_dwordx4 v31, v[60:63], s[10:11] nt

.LBB0_82:
	v_alignbit_b32 v12, v5, v4, 10
	v_and_b32_e32 v2, 0x400, v6
	v_mad_u64_u32 v[10:11], s[30:31], v7, v12, v[2:3]
	v_and_b32_e32 v14, 0x1ff8, v7
	v_and_b32_e32 v11, 0xff8, v10
	v_add_u32_e32 v10, v10, v12
	v_lshlrev_b32_e32 v2, 1, v14
	v_and_b32_e32 v14, 0xfff, v10
	v_add_u32_e32 v10, v10, v12
	v_lshl_add_u32 v11, v11, 1, 0
	v_lshl_add_u32 v14, v14, 1, 0
	v_and_b32_e32 v15, 0xffe, v10
	v_add_u32_e32 v10, v10, v12
	ds_read_u16 v11, v11
	ds_read_u16 v16, v14
	v_lshl_add_u32 v14, v15, 1, 0
	v_and_b32_e32 v15, 0xfff, v10
	v_add_u32_e32 v10, v10, v12
	v_lshl_add_u32 v15, v15, 1, 0
	v_and_b32_e32 v17, 0xffc, v10
	v_add_u32_e32 v10, v10, v12
	ds_read_u16 v18, v14
	ds_read_u16 v19, v15
	v_and_b32_e32 v15, 0xfff, v10
	v_add_u32_e32 v10, v10, v12
	v_lshl_add_u32 v14, v17, 1, 0
	v_and_b32_e32 v17, 0xffe, v10
	v_add_u32_e32 v10, v10, v12
	v_lshl_add_u32 v15, v15, 1, 0
	ds_read_u16 v12, v14
	ds_read_u16 v20, v15
	v_lshl_add_u32 v14, v17, 1, 0
	v_and_b32_e32 v10, 0xfff, v10
	v_lshl_add_u32 v10, v10, 1, 0
	ds_read_u16 v17, v14
	ds_read_u16 v21, v10
	v_lshrrev_b64 v[8:9], 10, v[4:5]
	v_lshl_add_u64 v[4:5], v[4:5], 0, s[4:5]
	v_lshlrev_b64 v[8:9], 14, v[8:9]
	v_cmp_lt_u64_e32 vcc, s[16:17], v[4:5]
	v_lshl_add_u64 v[8:9], s[6:7], 0, v[8:9]
	v_add_u32_e32 v6, s18, v6
	v_add_u32_e32 v7, s19, v7
	s_or_b64 s[10:11], vcc, s[10:11]
	v_lshl_add_u64 v[14:15], v[8:9], 0, v[2:3]
	s_waitcnt lgkmcnt(6)
	v_lshl_or_b32 v8, v16, 16, v11
	s_waitcnt lgkmcnt(4)
	v_lshl_or_b32 v9, v19, 16, v18
	s_waitcnt lgkmcnt(2)
	v_lshl_or_b32 v10, v20, 16, v12
	s_waitcnt lgkmcnt(0)
	v_lshl_or_b32 v11, v21, 16, v17
	global_store_dwordx4 v[14:15], v[8:11], off nt
	s_andn2_b64 exec, exec, s[10:11]
	s_cbranch_execnz .LBB0_82

.LBB0_92:
	s_or_b64 exec, exec, s[18:19]
	v_lshl_or_b32 v2, v2, 10, v10
	v_lshl_add_u64 v[6:7], v[6:7], 0, s[4:5]
	v_mad_u64_u32 v[8:9], s[18:19], v2, s49, v[4:5]
	v_lshlrev_b32_e32 v2, 1, v12
	v_cmp_lt_u64_e32 vcc, s[16:17], v[6:7]
	v_lshl_add_u64 v[8:9], v[8:9], 0, v[2:3]
	s_or_b64 s[10:11], vcc, s[10:11]
	s_waitcnt vmcnt(2)
	v_cvt_pk_bf16_f32 v14, v14, v15
	s_waitcnt vmcnt(0)
	v_cvt_pk_bf16_f32 v15, v16, v17
	v_cvt_pk_bf16_f32 v16, v18, v19
	v_cvt_pk_bf16_f32 v17, v20, v21
	global_store_dwordx4 v[8:9], v[14:17], off nt
	s_andn2_b64 exec, exec, s[10:11]
	s_cbranch_execz .LBB0_99

.LBB0_101:
	v_mul_hi_u32 v2, v4, s16
	v_sub_u32_e32 v8, v4, v2
	v_lshrrev_b32_e32 v8, 1, v8
	v_add_u32_e32 v2, v8, v2
	v_lshrrev_b32_e32 v2, 4, v2
	v_mul_lo_u32 v8, v2, 31
	v_mul_lo_u32 v2, v2, s17
	v_sub_u32_e32 v10, v4, v8
	v_lshl_add_u64 v[8:9], s[8:9], 0, v[2:3]
	v_lshl_add_u64 v[4:5], v[4:5], 0, s[4:5]
	v_lshlrev_b32_e32 v2, 3, v10
	v_cmp_lt_u64_e32 vcc, s[10:11], v[4:5]
	v_lshl_add_u64 v[8:9], v[8:9], 0, v[2:3]
	s_or_b64 s[6:7], vcc, s[6:7]
	v_add_co_u32_e32 v8, vcc, 0x54600000, v8
	s_nop 1
	v_addc_co_u32_e32 v9, vcc, 0, v9, vcc
	global_store_dwordx2 v[8:9], v[6:7], off offset:2056 nt
	s_andn2_b64 exec, exec, s[6:7]
	s_cbranch_execnz .LBB0_101

.LBB0_111:
	v_lshrrev_b64 v[14:15], 5, v[6:7]
	v_cvt_f64_u32_e32 v[16:17], v15
	v_cvt_f64_u32_e32 v[14:15], v14
	v_ldexp_f64 v[16:17], v[16:17], 32
	v_add_f64 v[14:15], v[16:17], v[14:15]
	v_mul_f64 v[14:15], v[2:3], v[14:15]
	v_mul_f64 v[16:17], v[14:15], s[16:17]
	v_rndne_f64_e32 v[16:17], v[16:17]
	v_fma_f64 v[14:15], v[14:15], s[16:17], -v[16:17]
	v_cvt_f32_f64_e32 v11, v[14:15]
	v_add_f32_e32 v11, v11, v11
	v_lshl_add_u64 v[6:7], v[6:7], 0, s[4:5]
	v_mul_f32_e64 v14, |v11|, 0.5
	v_cmp_lt_u64_e32 vcc, s[18:19], v[6:7]
	v_fract_f32_e32 v15, v14
	s_or_b64 s[10:11], vcc, s[10:11]
	v_add_f32_e32 v15, v15, v15
	v_cmp_neq_f32_e64 vcc, |v14|, s30
	v_cmp_gt_f32_e64 s[34:35], |v11|, 1.0
	v_and_b32_e32 v12, 0x7fffffff, v11
	v_cndmask_b32_e32 v14, 0, v15, vcc
	v_cndmask_b32_e64 v14, |v11|, v14, s[34:35]
	v_add_f32_e32 v15, v14, v14
	v_rndne_f32_e32 v15, v15
	v_fmac_f32_e32 v14, -0.5, v15
	v_cvt_i32_f32_e32 v15, v15
	v_mul_f32_e32 v16, v14, v14
	v_fmamk_f32 v17, v16, 0x3e75aa41, v8
	v_fmamk_f32 v19, v16, 0x3d4be544, v9
	v_fmaak_f32 v17, v16, v17, 0x40234736
	v_fmaak_f32 v19, v16, v19, 0xbfaad1da
	v_mul_f32_e32 v18, v14, v16
	v_fmaak_f32 v17, v16, v17, 0xc0a55e0e
	v_fmaak_f32 v19, v16, v19, 0x4081e0d3
	v_and_b32_e32 v20, 2, v15
	v_and_b32_e32 v21, 1, v15
	v_lshlrev_b32_e32 v15, 30, v15
	v_mul_f32_e32 v17, v18, v17
	v_fmaak_f32 v18, v16, v19, 0xc09de9e6
	v_xor_b32_e32 v12, v12, v11
	v_and_b32_e32 v15, 0x80000000, v15
	v_fmac_f32_e32 v17, 0x40490fdb, v14
	v_fma_f32 v14, v16, v18, 1.0
	v_cmp_eq_u32_e32 vcc, 0, v21
	v_xor_b32_e32 v12, v12, v15
	s_nop 0
	v_cndmask_b32_e64 v15, -v17, v14, vcc
	v_cndmask_b32_e32 v14, v14, v17, vcc
	v_cmp_eq_u32_e32 vcc, 0, v20
	v_xor_b32_e32 v12, v12, v14
	s_nop 0
	v_cndmask_b32_e64 v15, -v15, v15, vcc
	v_cmp_class_f32_e64 vcc, v11, s31
	s_nop 1
	v_cndmask_b32_e32 v14, v10, v15, vcc
	v_cndmask_b32_e32 v15, v10, v12, vcc
	global_store_dwordx2 v[4:5], v[14:15], off nt
	v_lshl_add_u64 v[4:5], v[4:5], 0, s[6:7]
	s_andn2_b64 exec, exec, s[10:11]
	s_cbranch_execnz .LBB0_111

.LBB0_114:
	v_cmp_gt_u64_e32 vcc, s[16:17], v[0:1]
	v_mov_b32_e32 v9, v5
	v_lshl_add_u64 v[10:11], v[2:3], 0, s[18:19]
	v_cndmask_b32_e64 v8, 24, 16, vcc
	v_lshl_add_u64 v[8:9], s[24:25], 0, v[8:9]
	global_load_dwordx2 v[8:9], v[8:9], off
	v_cndmask_b32_e32 v19, v11, v3, vcc
	v_cndmask_b32_e32 v18, v10, v2, vcc
	v_cndmask_b32_e32 v4, v6, v7, vcc
	v_lshl_add_u64 v[0:1], v[0:1], 0, s[4:5]
	v_cmp_lt_u64_e32 vcc, s[30:31], v[0:1]
	v_lshl_add_u64 v[2:3], v[2:3], 0, s[6:7]
	s_or_b64 s[10:11], vcc, s[10:11]
	s_waitcnt vmcnt(0)
	v_lshl_add_u64 v[20:21], v[18:19], 2, v[8:9]
	global_load_dwordx4 v[8:11], v[20:21], off
	global_load_dwordx4 v[14:17], v[20:21], off offset:16
	v_lshl_add_u64 v[20:21], s[8:9], 0, v[4:5]
	v_lshl_add_u64 v[18:19], v[18:19], 1, v[20:21]
	s_waitcnt vmcnt(1)
	v_cvt_pk_bf16_f32 v8, v8, v9
	v_cvt_pk_bf16_f32 v9, v10, v11
	s_waitcnt vmcnt(0)
	v_cvt_pk_bf16_f32 v10, v14, v15
	v_cvt_pk_bf16_f32 v11, v16, v17
	global_store_dwordx4 v[18:19], v[8:11], off nt
	s_andn2_b64 exec, exec, s[10:11]
	s_cbranch_execnz .LBB0_114

.LBB0_123:
	s_load_dwordx4 s[16:19], s[24:25], 0x98
	v_lshlrev_b64 v[8:9], 6, v[0:1]
	v_pk_mul_f32 v[38:39], v[2:3], v[2:3]
	v_mov_b32_e32 v40, v3
	v_mov_b32_e32 v42, v3
	s_waitcnt lgkmcnt(0)
	v_lshl_add_u64 v[24:25], s[18:19], 0, v[8:9]
	global_load_dwordx4 v[4:7], v[24:25], off
	v_lshl_add_u64 v[32:33], s[16:17], 0, v[8:9]
	global_load_dwordx4 v[8:11], v[32:33], off
	global_load_dwordx4 v[12:15], v[24:25], off offset:16
	global_load_dwordx4 v[16:19], v[32:33], off offset:16
	ds_read_b64 v[36:37], v50 offset:512
	global_load_dwordx4 v[20:23], v[24:25], off offset:48
	s_nop 0
	global_load_dwordx4 v[24:27], v[24:25], off offset:32
	s_nop 0
	global_load_dwordx4 v[28:31], v[32:33], off offset:48
	s_nop 0
	global_load_dwordx4 v[32:35], v[32:33], off offset:32
	v_mov_b32_e32 v43, v2
	v_pk_add_f32 v[2:3], v[38:39], v[38:39] op_sel:[0,1] op_sel_hi:[0,1]
	v_lshl_add_u64 v[0:1], v[0:1], 3, s[30:31]
	s_waitcnt lgkmcnt(0)
	v_add_f32_e32 v38, -1.0, v36
	v_pk_mul_f32 v[38:39], v[42:43], v[38:39] op_sel:[1,0] op_sel_hi:[0,0]
	v_pk_fma_f32 v[40:41], v[40:41], v[36:37], v[38:39] op_sel:[0,1,0]
	v_pk_fma_f32 v[36:37], v[42:43], v[36:37], v[38:39] op_sel:[0,1,0] neg_lo:[0,0,1] neg_hi:[0,0,1]
	v_div_scale_f32 v39, s[10:11], v2, v2, v40
	v_div_scale_f32 v36, s[10:11], v3, v3, v37
	v_rcp_f32_e32 v41, v36
	v_rcp_f32_e32 v42, v39
	v_div_scale_f32 v38, vcc, v37, v3, v37
	v_fma_f32 v48, -v36, v41, 1.0
	v_fma_f32 v62, -v39, v42, 1.0
	v_fmac_f32_e32 v41, v48, v41
	v_div_scale_f32 v43, s[10:11], v40, v2, v40
	v_fmac_f32_e32 v42, v62, v42
	v_mul_f32_e32 v48, v38, v41
	v_mul_f32_e32 v62, v43, v42
	v_fma_f32 v63, -v36, v48, v38
	v_fma_f32 v64, -v39, v62, v43
	v_fmac_f32_e32 v48, v63, v41
	v_fmac_f32_e32 v62, v64, v42
	v_fma_f32 v36, -v36, v48, v38
	v_fma_f32 v38, -v39, v62, v43
	v_div_fmas_f32 v36, v36, v41, v48
	s_mov_b64 vcc, s[10:11]
	v_div_fixup_f32 v37, v36, v3, v37
	v_div_fmas_f32 v3, v38, v42, v62
	v_div_fixup_f32 v36, v3, v2, v40
	s_waitcnt vmcnt(6)
	v_mov_b32_e32 v62, v11
	v_pk_mul_f32 v[38:39], v[4:5], v[36:37] op_sel:[0,1] op_sel_hi:[0,0]
	v_pk_mul_f32 v[40:41], v[36:37], v[4:5] op_sel:[1,1] op_sel_hi:[0,1]
	v_mov_b32_e32 v4, v9
	v_pk_mul_f32 v[42:43], v[36:37], v[6:7] op_sel:[1,0] op_sel_hi:[0,0]
	v_mov_b32_e32 v48, v7
	v_mov_b32_e32 v64, v11
	s_waitcnt vmcnt(5)
	v_pk_mul_f32 v[66:67], v[36:37], v[12:13] op_sel:[1,0] op_sel_hi:[0,0]
	v_pk_mul_f32 v[68:69], v[36:37], v[12:13] op_sel:[1,1] op_sel_hi:[0,1]
	s_waitcnt vmcnt(4)
	v_mov_b32_e32 v12, v17
	v_pk_fma_f32 v[2:3], v[8:9], v[36:37], v[38:39] neg_lo:[0,0,1] neg_hi:[0,0,1]
	v_pk_fma_f32 v[38:39], v[8:9], v[36:37], v[38:39] op_sel_hi:[0,1,1]
	v_pk_fma_f32 v[4:5], v[36:37], v[4:5], v[40:41] neg_lo:[0,0,1] neg_hi:[0,0,1]
	v_pk_fma_f32 v[8:9], v[36:37], v[8:9], v[40:41] op_sel:[0,1,0]
	v_pk_fma_f32 v[6:7], v[36:37], v[10:11], v[42:43] neg_lo:[0,0,1] neg_hi:[0,0,1]
	v_pk_fma_f32 v[40:41], v[36:37], v[10:11], v[42:43] op_sel_hi:[1,0,1]
	v_pk_mul_f32 v[42:43], v[36:37], v[48:49] op_sel:[1,0] op_sel_hi:[0,0]
	v_pk_fma_f32 v[10:11], v[36:37], v[16:17], v[66:67] neg_lo:[0,0,1] neg_hi:[0,0,1]
	v_pk_fma_f32 v[66:67], v[36:37], v[16:17], v[66:67] op_sel_hi:[1,0,1]
	v_pk_fma_f32 v[12:13], v[36:37], v[12:13], v[68:69] neg_lo:[0,0,1] neg_hi:[0,0,1]
	v_pk_fma_f32 v[16:17], v[36:37], v[16:17], v[68:69] op_sel:[0,1,0]
	v_mov_b32_e32 v3, v39
	v_mov_b32_e32 v5, v9
	v_pk_fma_f32 v[8:9], v[36:37], v[62:63], v[42:43] neg_lo:[0,0,1] neg_hi:[0,0,1]
	v_pk_fma_f32 v[38:39], v[36:37], v[64:65], v[42:43] op_sel_hi:[1,0,1]
	v_mov_b32_e32 v7, v41
	v_mov_b32_e32 v11, v67
	v_mov_b32_e32 v13, v17
	ds_write_b128 v58, v[2:5] offset:17408
	v_mov_b32_e32 v9, v39
	s_waitcnt vmcnt(2)
	v_pk_mul_f32 v[4:5], v[36:37], v[24:25] op_sel:[1,0] op_sel_hi:[0,0]
	ds_write_b128 v58, v[10:13] offset:17440
	ds_write_b128 v58, v[6:9] offset:17424
	s_waitcnt vmcnt(0)
	v_pk_fma_f32 v[2:3], v[36:37], v[32:33], v[4:5] neg_lo:[0,0,1] neg_hi:[0,0,1]
	v_pk_fma_f32 v[6:7], v[36:37], v[32:33], v[4:5] op_sel_hi:[1,0,1]
	v_pk_mul_f32 v[8:9], v[36:37], v[24:25] op_sel:[1,1] op_sel_hi:[0,1]
	v_mov_b32_e32 v4, v33
	v_pk_fma_f32 v[4:5], v[36:37], v[4:5], v[8:9] neg_lo:[0,0,1] neg_hi:[0,0,1]
	v_pk_fma_f32 v[8:9], v[36:37], v[32:33], v[8:9] op_sel:[0,1,0]
	v_mov_b32_e32 v3, v7
	v_mov_b32_e32 v5, v9
	ds_write_b128 v58, v[2:5] offset:17472
	v_pk_mul_f32 v[4:5], v[36:37], v[26:27] op_sel:[1,0] op_sel_hi:[0,0]
	v_pk_fma_f32 v[2:3], v[36:37], v[34:35], v[4:5] neg_lo:[0,0,1] neg_hi:[0,0,1]
	v_pk_fma_f32 v[6:7], v[36:37], v[34:35], v[4:5] op_sel_hi:[1,0,1]
	v_mov_b32_e32 v4, v27
	v_pk_mul_f32 v[8:9], v[36:37], v[4:5] op_sel:[1,0] op_sel_hi:[0,0]
	v_mov_b32_e32 v4, v35
	v_mov_b32_e32 v6, v35
	v_pk_fma_f32 v[4:5], v[36:37], v[4:5], v[8:9] neg_lo:[0,0,1] neg_hi:[0,0,1]
	v_pk_fma_f32 v[8:9], v[36:37], v[6:7], v[8:9] op_sel_hi:[1,0,1]
	v_mov_b32_e32 v3, v7
	v_mov_b32_e32 v5, v9
	ds_write_b128 v58, v[2:5] offset:17488
	v_pk_mul_f32 v[4:5], v[36:37], v[20:21] op_sel:[1,0] op_sel_hi:[0,0]
	v_pk_fma_f32 v[2:3], v[36:37], v[28:29], v[4:5] neg_lo:[0,0,1] neg_hi:[0,0,1]
	v_pk_fma_f32 v[6:7], v[36:37], v[28:29], v[4:5] op_sel_hi:[1,0,1]
	v_pk_mul_f32 v[8:9], v[36:37], v[20:21] op_sel:[1,1] op_sel_hi:[0,1]
	v_mov_b32_e32 v4, v29
	v_pk_fma_f32 v[4:5], v[36:37], v[4:5], v[8:9] neg_lo:[0,0,1] neg_hi:[0,0,1]
	v_pk_fma_f32 v[8:9], v[36:37], v[28:29], v[8:9] op_sel:[0,1,0]
	v_mov_b32_e32 v3, v7
	v_mov_b32_e32 v5, v9
	ds_write_b128 v58, v[2:5] offset:17504
	v_pk_mul_f32 v[4:5], v[36:37], v[22:23] op_sel:[1,0] op_sel_hi:[0,0]
	v_mov_b32_e32 v72, v15
	v_pk_fma_f32 v[2:3], v[36:37], v[30:31], v[4:5] neg_lo:[0,0,1] neg_hi:[0,0,1]
	v_pk_fma_f32 v[6:7], v[36:37], v[30:31], v[4:5] op_sel_hi:[1,0,1]
	v_mov_b32_e32 v4, v23
	v_pk_mul_f32 v[70:71], v[36:37], v[14:15] op_sel:[1,0] op_sel_hi:[0,0]
	v_mov_b32_e32 v74, v19
	v_mov_b32_e32 v76, v19
	v_pk_mul_f32 v[68:69], v[36:37], v[72:73] op_sel:[1,0] op_sel_hi:[0,0]
	v_pk_mul_f32 v[8:9], v[36:37], v[4:5] op_sel:[1,0] op_sel_hi:[0,0]
	v_mov_b32_e32 v4, v31
	v_mov_b32_e32 v6, v31
	v_pk_fma_f32 v[14:15], v[36:37], v[18:19], v[70:71] neg_lo:[0,0,1] neg_hi:[0,0,1]
	v_pk_fma_f32 v[18:19], v[36:37], v[18:19], v[70:71] op_sel_hi:[1,0,1]
	v_pk_fma_f32 v[16:17], v[36:37], v[74:75], v[68:69] neg_lo:[0,0,1] neg_hi:[0,0,1]
	v_pk_fma_f32 v[40:41], v[36:37], v[76:77], v[68:69] op_sel_hi:[1,0,1]
	v_pk_fma_f32 v[4:5], v[36:37], v[4:5], v[8:9] neg_lo:[0,0,1] neg_hi:[0,0,1]
	v_pk_fma_f32 v[8:9], v[36:37], v[6:7], v[8:9] op_sel_hi:[1,0,1]
	v_mov_b32_e32 v15, v19
	v_mov_b32_e32 v17, v41
	v_mov_b32_e32 v3, v7
	v_mov_b32_e32 v5, v9
	ds_write_b128 v58, v[14:17] offset:17456
	ds_write_b128 v58, v[2:5] offset:17520
	ds_read_b64 v[2:3], v50 offset:8192
	s_waitcnt lgkmcnt(0)
	global_store_dwordx2 v[0:1], v[2:3], off nt

.LBB0_131:
	v_bfe_u32 v5, v0, 4, 4
	v_ashrrev_i32_e32 v2, 5, v1
	v_and_b32_e32 v4, 0xf8, v0
	v_and_b32_e32 v3, 8, v0
	v_ashrrev_i32_e32 v6, 12, v1
	v_xor_b32_e32 v9, 15, v5
	v_cmp_gt_u32_e64 s[10:11], s59, v1
	v_add_u32_e32 v7, 0x200, v1
	v_and_b32_e32 v8, 63, v2
	v_mul_i32_i24_e32 v10, 17, v6
	v_lshlrev_b32_e32 v11, 3, v3
	v_ashrrev_i32_e32 v3, 31, v2
	v_lshlrev_b32_e32 v48, 1, v4
	v_cndmask_b32_e64 v4, v5, v9, s[10:11]
	v_and_b32_e32 v38, 0x800, v1
	v_cmp_lt_i32_e32 vcc, s61, v1
	v_lshl_add_u32 v6, v6, 13, 0
	v_mov_b32_e32 v1, v7
	v_lshlrev_b32_e32 v5, 3, v8
	v_lshlrev_b32_e32 v7, 7, v8
	v_lshlrev_b64 v[2:3], 9, v[2:3]
	v_add_lshl_u32 v4, v4, v10, 9
	v_add3_u32 v16, v6, v7, v11
	v_lshl_add_u64 v[14:15], s[16:17], 0, v[2:3]
	v_add3_u32 v17, 0, v4, v5
	ds_read_b128 v[2:5], v16 offset:17424
	ds_read_b128 v[6:9], v16 offset:17440
	ds_read_b128 v[10:13], v16 offset:17456
	v_lshl_add_u64 v[18:19], v[14:15], 0, v[48:49]
	ds_read_b64 v[20:21], v17
	ds_read_b128 v[14:17], v16 offset:17408
	s_or_b64 s[18:19], vcc, s[18:19]
	v_cmp_eq_u32_e32 vcc, 0, v38
	v_add_u32_e32 v0, 0x1000, v0
	s_waitcnt lgkmcnt(1)
	v_pk_mul_f32 v[26:27], v[20:21], v[2:3] op_sel:[0,1] op_sel_hi:[1,0]
	v_pk_mul_f32 v[2:3], v[20:21], v[2:3]
	v_pk_mul_f32 v[28:29], v[20:21], v[4:5] op_sel:[0,1] op_sel_hi:[1,0]
	v_pk_mul_f32 v[4:5], v[20:21], v[4:5]
	v_pk_mul_f32 v[30:31], v[20:21], v[6:7] op_sel:[0,1] op_sel_hi:[1,0]
	v_pk_mul_f32 v[6:7], v[20:21], v[6:7]
	v_pk_mul_f32 v[32:33], v[20:21], v[8:9] op_sel:[0,1] op_sel_hi:[1,0]
	v_pk_mul_f32 v[8:9], v[20:21], v[8:9]
	s_waitcnt lgkmcnt(0)
	v_pk_mul_f32 v[22:23], v[20:21], v[14:15] op_sel:[0,1] op_sel_hi:[1,0]
	v_pk_mul_f32 v[14:15], v[20:21], v[14:15]
	v_pk_mul_f32 v[24:25], v[20:21], v[16:17] op_sel:[0,1] op_sel_hi:[1,0]
	v_pk_mul_f32 v[16:17], v[20:21], v[16:17]
	v_pk_mul_f32 v[34:35], v[20:21], v[10:11] op_sel:[0,1] op_sel_hi:[1,0]
	v_pk_mul_f32 v[10:11], v[20:21], v[10:11]
	v_pk_mul_f32 v[36:37], v[20:21], v[12:13] op_sel:[0,1] op_sel_hi:[1,0]
	v_pk_mul_f32 v[12:13], v[20:21], v[12:13]
	v_sub_f32_e32 v2, v2, v3
	v_add_f32_e32 v3, v28, v29
	v_sub_f32_e32 v4, v4, v5
	v_add_f32_e32 v5, v30, v31
	v_sub_f32_e32 v6, v6, v7
	v_add_f32_e32 v7, v32, v33
	v_sub_f32_e32 v8, v8, v9
	v_add_f32_e32 v20, v22, v23
	v_sub_f32_e32 v14, v14, v15
	v_add_f32_e32 v15, v24, v25
	v_sub_f32_e32 v16, v16, v17
	v_add_f32_e32 v17, v26, v27
	v_add_f32_e32 v9, v34, v35
	v_sub_f32_e32 v10, v10, v11
	v_add_f32_e32 v11, v36, v37
	v_sub_f32_e32 v12, v12, v13
	v_cndmask_b32_e32 v3, v3, v4, vcc
	v_cndmask_b32_e32 v4, v5, v6, vcc
	v_cndmask_b32_e32 v5, v7, v8, vcc
	v_cndmask_b32_e32 v13, v20, v14, vcc
	v_cndmask_b32_e32 v14, v15, v16, vcc
	v_cndmask_b32_e32 v15, v17, v2, vcc
	v_cndmask_b32_e32 v6, v9, v10, vcc
	v_cndmask_b32_e32 v7, v11, v12, vcc
	v_cvt_pk_bf16_f32 v2, v13, v14
	v_cvt_pk_bf16_f32 v3, v15, v3
	v_cvt_pk_bf16_f32 v4, v4, v5
	v_cvt_pk_bf16_f32 v5, v6, v7
	global_store_dwordx4 v[18:19], v[2:5], off nt
	s_andn2_b64 exec, exec, s[18:19]
	s_cbranch_execnz .LBB0_131

.LBB0_135:
	s_or_b64 exec, exec, s[42:43]
	s_waitcnt lgkmcnt(0)
	v_cvt_pk_bf16_f32 v8, v1, v7
	v_ashrrev_i32_e32 v1, 31, v0
	v_lshlrev_b64 v[0:1], 10, v[0:1]
	v_lshl_add_u64 v[0:1], s[18:19], 0, v[0:1]
	v_lshlrev_b32_e32 v48, 1, v6
	v_lshl_add_u64 v[0:1], v[0:1], 0, v[48:49]
	v_cvt_pk_bf16_f32 v9, v12, v14
	v_cvt_pk_bf16_f32 v10, v15, v16
	v_cvt_pk_bf16_f32 v11, v17, v18
	global_store_dwordx4 v[0:1], v[8:11], off nt
	v_add_u32_e32 v0, 0x200, v5
	v_cmp_lt_i32_e32 vcc, s64, v5
	v_add_u32_e32 v4, 0x1000, v4
	s_or_b64 s[40:41], vcc, s[40:41]
	v_mov_b32_e32 v5, v0
	s_andn2_b64 exec, exec, s[40:41]
	s_cbranch_execz .LBB0_117

.LBB0_281:
	v_pk_mul_f32 v[0:1], v[190:191], v[190:191]
	v_pk_mul_f32 v[2:3], v[192:193], v[192:193]
	v_pk_fma_f32 v[0:1], v[194:195], v[194:195], v[0:1]
	v_pk_fma_f32 v[2:3], v[196:197], v[196:197], v[2:3]
	v_pk_add_f32 v[0:1], v[0:1], v[0:1] op_sel_hi:[0,1]
	v_mul_f32_e32 v201, v92, v92
	v_mul_f32_e32 v5, v93, v93
	v_mul_f32_e32 v0, v94, v94
	v_mov_b32_e32 v4, v200
	v_pk_add_f32 v[2:3], v[2:3], v[2:3] op_sel_hi:[0,1]
	v_pk_fma_f32 v[6:7], v[94:95], v[94:95], v[0:1] op_sel_hi:[1,1,0]
	v_pk_add_f32 v[4:5], v[200:201], v[4:5]
	v_mul_f32_e32 v6, v217, v217
	v_mul_f32_e32 v2, v205, v205
	v_mul_f32_e32 v0, v199, v199
	v_mul_f32_e32 v8, v200, v200
	v_mov_b32_e32 v9, v5
	v_pk_add_f32 v[4:5], v[8:9], v[6:7]
	v_pk_add_f32 v[0:1], v[2:3], v[0:1]
	v_pk_mul_f32 v[2:3], v[174:175], v[174:175]
	v_pk_add_f32 v[0:1], v[4:5], v[0:1]
	v_pk_fma_f32 v[2:3], v[188:189], v[188:189], v[2:3]
	v_pk_add_f32 v[0:1], v[0:1], v[0:1] op_sel_hi:[0,1]
	v_mul_f32_e32 v205, v104, v104
	v_mul_f32_e32 v5, v105, v105
	v_mul_f32_e32 v0, v106, v106
	v_mov_b32_e32 v4, v204
	v_pk_add_f32 v[2:3], v[2:3], v[2:3] op_sel_hi:[0,1]
	v_pk_fma_f32 v[6:7], v[106:107], v[106:107], v[0:1] op_sel_hi:[1,1,0]
	v_pk_add_f32 v[4:5], v[204:205], v[4:5]
	v_mul_f32_e32 v6, v229, v229
	v_mul_f32_e32 v2, v228, v228
	v_mul_f32_e32 v0, v227, v227
	v_mul_f32_e32 v8, v204, v204
	v_mov_b32_e32 v9, v5
	v_pk_add_f32 v[4:5], v[8:9], v[6:7]
	v_pk_add_f32 v[0:1], v[2:3], v[0:1]
	v_pk_mul_f32 v[2:3], v[170:171], v[170:171]
	v_pk_add_f32 v[0:1], v[4:5], v[0:1]
	v_pk_fma_f32 v[2:3], v[172:173], v[172:173], v[2:3]
	v_pk_add_f32 v[0:1], v[0:1], v[0:1] op_sel_hi:[0,1]
	v_mul_f32_e32 v199, v116, v116
	v_mul_f32_e32 v5, v117, v117
	v_mul_f32_e32 v0, v118, v118
	v_mov_b32_e32 v4, v198
	v_pk_add_f32 v[2:3], v[2:3], v[2:3] op_sel_hi:[0,1]
	v_pk_fma_f32 v[6:7], v[118:119], v[118:119], v[0:1] op_sel_hi:[1,1,0]
	v_pk_add_f32 v[4:5], v[198:199], v[4:5]
	v_mul_f32_e32 v6, v216, v216
	v_mul_f32_e32 v2, v207, v207
	v_mul_f32_e32 v0, v203, v203
	v_mul_f32_e32 v8, v198, v198
	v_mov_b32_e32 v9, v5
	v_pk_add_f32 v[4:5], v[8:9], v[6:7]
	v_pk_add_f32 v[0:1], v[2:3], v[0:1]
	v_pk_mul_f32 v[2:3], v[162:163], v[162:163]
	v_pk_add_f32 v[0:1], v[4:5], v[0:1]
	v_pk_fma_f32 v[2:3], v[164:165], v[164:165], v[2:3]
	v_pk_add_f32 v[0:1], v[0:1], v[0:1] op_sel_hi:[0,1]
	v_mul_f32_e32 v203, v128, v128
	v_mul_f32_e32 v5, v129, v129
	v_mul_f32_e32 v0, v130, v130
	v_mov_b32_e32 v4, v202
	v_pk_add_f32 v[2:3], v[2:3], v[2:3] op_sel_hi:[0,1]
	v_pk_fma_f32 v[6:7], v[130:131], v[130:131], v[0:1] op_sel_hi:[1,1,0]
	v_pk_add_f32 v[4:5], v[202:203], v[4:5]
	v_mul_f32_e32 v6, v226, v226
	v_mul_f32_e32 v2, v219, v219
	v_mul_f32_e32 v0, v218, v218
	v_mul_f32_e32 v8, v202, v202
	v_mov_b32_e32 v9, v5
	v_pk_add_f32 v[4:5], v[8:9], v[6:7]
	v_pk_add_f32 v[0:1], v[2:3], v[0:1]
	v_pk_mul_f32 v[2:3], v[166:167], v[166:167]
	v_pk_add_f32 v[0:1], v[4:5], v[0:1]
	v_pk_fma_f32 v[2:3], v[168:169], v[168:169], v[2:3]
	v_pk_add_f32 v[0:1], v[0:1], v[0:1] op_sel_hi:[0,1]
	v_mul_f32_e32 v207, v136, v136
	v_mul_f32_e32 v5, v137, v137
	v_mul_f32_e32 v0, v138, v138
	v_mov_b32_e32 v4, v206
	v_pk_add_f32 v[2:3], v[2:3], v[2:3] op_sel_hi:[0,1]
	v_pk_fma_f32 v[6:7], v[138:139], v[138:139], v[0:1] op_sel_hi:[1,1,0]
	v_pk_add_f32 v[4:5], v[206:207], v[4:5]
	v_mul_f32_e32 v6, v231, v231
	v_mul_f32_e32 v2, v230, v230
	v_mul_f32_e32 v0, v232, v232
	v_mul_f32_e32 v8, v206, v206
	v_mov_b32_e32 v9, v5
	v_pk_add_f32 v[4:5], v[8:9], v[6:7]
	v_pk_add_f32 v[0:1], v[2:3], v[0:1]
	s_add_i32 s52, s52, 2
	v_pk_add_f32 v[0:1], v[4:5], v[0:1]
	ds_read_b128 v[2:5], v214
	ds_read_b128 v[6:9], v214 offset:16384
	v_add_f32_e32 v0, v0, v1
	ds_bpermute_b32 v1, v208, v0
	ds_read_b128 v[10:13], v214 offset:1024
	ds_read_b128 v[14:17], v214 offset:17408
	s_cmp_eq_u32 s52, 8
	s_waitcnt lgkmcnt(2)
	v_add_f32_e32 v0, v0, v1
	ds_bpermute_b32 v1, v209, v0
	s_waitcnt lgkmcnt(0)
	v_add_f32_e32 v0, v0, v1
	ds_bpermute_b32 v1, v210, v0
	s_waitcnt lgkmcnt(0)
	v_add_f32_e32 v0, v0, v1
	ds_bpermute_b32 v1, v211, v0
	s_waitcnt lgkmcnt(0)
	v_add_f32_e32 v0, v0, v1
	ds_bpermute_b32 v1, v212, v0
	s_waitcnt lgkmcnt(0)
	v_add_f32_e32 v0, v0, v1
	ds_bpermute_b32 v1, v213, v0
	s_waitcnt lgkmcnt(0)
	v_add_f32_e32 v0, v0, v1
	v_fmamk_f32 v0, v0, 0x39800000, v221
	v_mul_f32_e32 v1, 0x4b800000, v0
	v_cmp_gt_f32_e32 vcc, s42, v0
	s_nop 1
	v_cndmask_b32_e32 v0, v0, v1, vcc
	v_rsq_f32_e32 v0, v0
	s_nop 0
	v_mul_f32_e32 v1, 0x45800000, v0
	v_cndmask_b32_e32 v0, v0, v1, vcc
	v_pk_mul_f32 v[18:19], v[32:33], v[0:1] op_sel_hi:[1,0]
	v_pk_mul_f32 v[20:21], v[34:35], v[0:1] op_sel_hi:[1,0]
	v_pk_fma_f32 v[2:3], v[2:3], v[18:19], v[6:7]
	v_pk_fma_f32 v[4:5], v[4:5], v[20:21], v[8:9]
	v_pk_mul_f32 v[6:7], v[24:25], v[0:1] op_sel_hi:[1,0]
	v_pk_mul_f32 v[8:9], v[26:27], v[0:1] op_sel_hi:[1,0]
	v_lshl_add_u64 v[18:19], s[24:25], 1, v[156:157]
	v_pk_fma_f32 v[8:9], v[12:13], v[8:9], v[16:17]
	v_pk_fma_f32 v[6:7], v[10:11], v[6:7], v[14:15]
	v_cvt_pk_bf16_f32 v2, v2, v3
	v_cvt_pk_bf16_f32 v3, v4, v5
	v_pk_mul_f32 v[20:21], v[144:145], v[0:1] op_sel_hi:[1,0]
	v_cvt_pk_bf16_f32 v4, v6, v7
	v_cvt_pk_bf16_f32 v5, v8, v9
	global_store_dwordx4 v[18:19], v[2:5], off nt
	ds_read_b128 v[2:5], v214 offset:2048
	ds_read_b128 v[6:9], v214 offset:18432
	ds_read_b128 v[10:13], v214 offset:3072
	ds_read_b128 v[14:17], v214 offset:19456
	v_pk_mul_f32 v[22:23], v[146:147], v[0:1] op_sel_hi:[1,0]
	s_waitcnt lgkmcnt(2)
	v_pk_fma_f32 v[2:3], v[2:3], v[20:21], v[6:7]
	v_pk_fma_f32 v[4:5], v[4:5], v[22:23], v[8:9]
	v_pk_mul_f32 v[6:7], v[72:73], v[0:1] op_sel_hi:[1,0]
	v_pk_mul_f32 v[8:9], v[74:75], v[0:1] op_sel_hi:[1,0]
	s_waitcnt lgkmcnt(0)
	v_pk_fma_f32 v[6:7], v[10:11], v[6:7], v[14:15]
	v_pk_fma_f32 v[8:9], v[12:13], v[8:9], v[16:17]
	v_cvt_pk_bf16_f32 v2, v2, v3
	v_cvt_pk_bf16_f32 v3, v4, v5
	v_cvt_pk_bf16_f32 v4, v6, v7
	v_pk_mul_f32 v[20:21], v[76:77], v[0:1] op_sel_hi:[1,0]
	v_cvt_pk_bf16_f32 v5, v8, v9
	global_store_dwordx4 v[18:19], v[2:5], off offset:1024 nt
	ds_read_b128 v[2:5], v214 offset:4096
	ds_read_b128 v[6:9], v214 offset:20480
	ds_read_b128 v[10:13], v214 offset:5120
	ds_read_b128 v[14:17], v214 offset:21504
	v_pk_mul_f32 v[22:23], v[78:79], v[0:1] op_sel_hi:[1,0]
	s_waitcnt lgkmcnt(2)
	v_pk_fma_f32 v[2:3], v[2:3], v[20:21], v[6:7]
	v_pk_fma_f32 v[4:5], v[4:5], v[22:23], v[8:9]
	v_pk_mul_f32 v[6:7], v[140:141], v[0:1] op_sel_hi:[1,0]
	v_pk_mul_f32 v[8:9], v[142:143], v[0:1] op_sel_hi:[1,0]
	s_waitcnt lgkmcnt(0)
	v_pk_fma_f32 v[6:7], v[10:11], v[6:7], v[14:15]
	v_pk_fma_f32 v[8:9], v[12:13], v[8:9], v[16:17]
	v_cvt_pk_bf16_f32 v2, v2, v3
	v_cvt_pk_bf16_f32 v3, v4, v5
	v_cvt_pk_bf16_f32 v4, v6, v7
	v_pk_mul_f32 v[20:21], v[84:85], v[0:1] op_sel_hi:[1,0]
	v_cvt_pk_bf16_f32 v5, v8, v9
	global_store_dwordx4 v[18:19], v[2:5], off offset:2048 nt
	ds_read_b128 v[2:5], v214 offset:6144
	ds_read_b128 v[6:9], v214 offset:22528
	ds_read_b128 v[10:13], v214 offset:7168
	ds_read_b128 v[14:17], v214 offset:23552
	v_pk_mul_f32 v[22:23], v[86:87], v[0:1] op_sel_hi:[1,0]
	s_waitcnt lgkmcnt(2)
	v_pk_fma_f32 v[2:3], v[20:21], v[2:3], v[6:7]
	v_pk_fma_f32 v[4:5], v[22:23], v[4:5], v[8:9]
	v_pk_mul_f32 v[6:7], v[80:81], v[0:1] op_sel_hi:[1,0]
	v_pk_mul_f32 v[8:9], v[82:83], v[0:1] op_sel_hi:[1,0]
	s_waitcnt lgkmcnt(0)
	v_pk_fma_f32 v[6:7], v[6:7], v[10:11], v[14:15]
	v_pk_fma_f32 v[8:9], v[8:9], v[12:13], v[16:17]
	v_cvt_pk_bf16_f32 v2, v2, v3
	v_cvt_pk_bf16_f32 v3, v4, v5
	v_cvt_pk_bf16_f32 v4, v6, v7
	v_pk_mul_f32 v[20:21], v[132:133], v[0:1] op_sel_hi:[1,0]
	v_cvt_pk_bf16_f32 v5, v8, v9
	global_store_dwordx4 v[18:19], v[2:5], off offset:3072 nt
	ds_read_b128 v[2:5], v214 offset:8192
	ds_read_b128 v[6:9], v214 offset:24576
	ds_read_b128 v[10:13], v214 offset:9216
	ds_read_b128 v[14:17], v214 offset:25600
	v_pk_mul_f32 v[22:23], v[134:135], v[0:1] op_sel_hi:[1,0]
	v_add_co_u32_e32 v18, vcc, s46, v18
	s_waitcnt lgkmcnt(2)
	v_pk_fma_f32 v[4:5], v[22:23], v[4:5], v[8:9]
	v_pk_fma_f32 v[2:3], v[20:21], v[2:3], v[6:7]
	v_pk_mul_f32 v[6:7], v[88:89], v[0:1] op_sel_hi:[1,0]
	v_pk_mul_f32 v[8:9], v[90:91], v[0:1] op_sel_hi:[1,0]
	v_addc_co_u32_e32 v19, vcc, 0, v19, vcc
	s_waitcnt lgkmcnt(0)
	v_pk_fma_f32 v[8:9], v[8:9], v[12:13], v[16:17]
	v_pk_fma_f32 v[6:7], v[6:7], v[10:11], v[14:15]
	v_cvt_pk_bf16_f32 v2, v2, v3
	v_cvt_pk_bf16_f32 v3, v4, v5
	v_pk_mul_f32 v[20:21], v[96:97], v[0:1] op_sel_hi:[1,0]
	v_cvt_pk_bf16_f32 v4, v6, v7
	v_cvt_pk_bf16_f32 v5, v8, v9
	global_store_dwordx4 v[18:19], v[2:5], off nt
	ds_read_b128 v[2:5], v214 offset:10240
	ds_read_b128 v[6:9], v214 offset:26624
	ds_read_b128 v[10:13], v214 offset:11264
	ds_read_b128 v[14:17], v214 offset:27648
	v_pk_mul_f32 v[22:23], v[98:99], v[0:1] op_sel_hi:[1,0]
	s_waitcnt lgkmcnt(2)
	v_pk_fma_f32 v[2:3], v[20:21], v[2:3], v[6:7]
	v_pk_fma_f32 v[4:5], v[22:23], v[4:5], v[8:9]
	v_pk_mul_f32 v[6:7], v[124:125], v[0:1] op_sel_hi:[1,0]
	v_pk_mul_f32 v[8:9], v[126:127], v[0:1] op_sel_hi:[1,0]
	s_waitcnt lgkmcnt(0)
	v_pk_fma_f32 v[6:7], v[6:7], v[10:11], v[14:15]
	v_pk_fma_f32 v[8:9], v[8:9], v[12:13], v[16:17]
	v_cvt_pk_bf16_f32 v2, v2, v3
	v_cvt_pk_bf16_f32 v3, v4, v5
	v_cvt_pk_bf16_f32 v4, v6, v7
	v_pk_mul_f32 v[20:21], v[100:101], v[0:1] op_sel_hi:[1,0]
	v_cvt_pk_bf16_f32 v5, v8, v9
	global_store_dwordx4 v[18:19], v[2:5], off offset:1024 nt
	ds_read_b128 v[2:5], v214 offset:12288
	ds_read_b128 v[6:9], v214 offset:28672
	ds_read_b128 v[10:13], v214 offset:13312
	ds_read_b128 v[14:17], v214 offset:29696
	v_pk_mul_f32 v[22:23], v[102:103], v[0:1] op_sel_hi:[1,0]
	s_waitcnt lgkmcnt(2)
	v_pk_fma_f32 v[2:3], v[20:21], v[2:3], v[6:7]
	v_pk_fma_f32 v[4:5], v[22:23], v[4:5], v[8:9]
	v_pk_mul_f32 v[6:7], v[112:113], v[0:1] op_sel_hi:[1,0]
	v_pk_mul_f32 v[8:9], v[114:115], v[0:1] op_sel_hi:[1,0]
	s_waitcnt lgkmcnt(0)
	v_pk_fma_f32 v[6:7], v[6:7], v[10:11], v[14:15]
	v_pk_fma_f32 v[8:9], v[8:9], v[12:13], v[16:17]
	v_cvt_pk_bf16_f32 v2, v2, v3
	v_cvt_pk_bf16_f32 v3, v4, v5
	v_cvt_pk_bf16_f32 v4, v6, v7
	v_pk_mul_f32 v[20:21], v[120:121], v[0:1] op_sel_hi:[1,0]
	v_cvt_pk_bf16_f32 v5, v8, v9
	global_store_dwordx4 v[18:19], v[2:5], off offset:2048 nt
	ds_read_b128 v[2:5], v214 offset:14336
	ds_read_b128 v[6:9], v214 offset:30720
	ds_read_b128 v[10:13], v214 offset:15360
	ds_read_b128 v[14:17], v214 offset:31744
	v_pk_mul_f32 v[22:23], v[122:123], v[0:1] op_sel_hi:[1,0]
	s_waitcnt lgkmcnt(2)
	v_pk_fma_f32 v[2:3], v[20:21], v[2:3], v[6:7]
	v_pk_mul_f32 v[6:7], v[108:109], v[0:1] op_sel_hi:[1,0]
	v_pk_mul_f32 v[0:1], v[110:111], v[0:1] op_sel_hi:[1,0]
	v_pk_fma_f32 v[4:5], v[22:23], v[4:5], v[8:9]
	s_waitcnt lgkmcnt(0)
	v_pk_fma_f32 v[8:9], v[0:1], v[12:13], v[16:17]
	v_pk_fma_f32 v[6:7], v[6:7], v[10:11], v[14:15]
	v_cvt_pk_bf16_f32 v0, v2, v3
	v_cvt_pk_bf16_f32 v1, v4, v5
	s_nop 0
	v_cvt_pk_bf16_f32 v2, v6, v7
	v_cvt_pk_bf16_f32 v3, v8, v9
	global_store_dwordx4 v[18:19], v[0:3], off offset:3072 nt
	s_cbranch_scc1 .LBB0_275

.LBB0_285:
	s_lshl_b64 s[10:11], s[24:25], 1
	s_add_u32 s26, s35, s10
	s_addc_u32 s27, s48, s11
	s_add_u32 s28, s49, s10
	s_addc_u32 s29, s50, s11
	v_lshl_add_u64 v[80:81], s[28:29], 0, v[176:177]
	global_load_dwordx4 v[44:47], v[80:81], off
	v_lshl_add_u64 v[100:101], s[26:27], 0, v[176:177]
	v_lshl_add_u64 v[108:109], s[28:29], 0, v[152:153]
	v_lshl_add_u64 v[128:129], s[26:27], 0, v[152:153]
	s_waitcnt vmcnt(0)
	v_lshlrev_b32_e32 v48, 16, v44
	v_and_b32_e32 v49, 0xffff0000, v44
	v_lshlrev_b32_e32 v44, 16, v45
	v_and_b32_e32 v45, 0xffff0000, v45
	v_pk_add_f32 v[50:51], v[2:3], v[44:45]
	v_lshlrev_b32_e32 v44, 16, v46
	v_and_b32_e32 v45, 0xffff0000, v46
	v_lshlrev_b32_e32 v46, 16, v47
	v_and_b32_e32 v47, 0xffff0000, v47
	v_pk_add_f32 v[48:49], v[0:1], v[48:49]
	v_pk_add_f32 v[46:47], v[6:7], v[46:47]
	v_pk_add_f32 v[44:45], v[4:5], v[44:45]
	v_cvt_pk_bf16_f32 v72, v48, v49
	v_cvt_pk_bf16_f32 v73, v50, v51
	v_mov_b32_e32 v191, v51
	v_cvt_pk_bf16_f32 v74, v44, v45
	v_cvt_pk_bf16_f32 v75, v46, v47
	global_store_dwordx4 v[100:101], v[72:75], off nt
	global_load_dwordx4 v[72:75], v[80:81], off offset:1024
	v_mov_b32_e32 v190, v49
	v_mov_b32_e32 v195, v50
	v_mov_b32_e32 v194, v48
	v_mov_b32_e32 v193, v47
	v_mov_b32_e32 v192, v45
	v_mov_b32_e32 v197, v46
	v_mov_b32_e32 v196, v44
	s_waitcnt vmcnt(0)
	v_lshlrev_b32_e32 v76, 16, v72
	v_and_b32_e32 v77, 0xffff0000, v72
	v_lshlrev_b32_e32 v72, 16, v73
	v_and_b32_e32 v73, 0xffff0000, v73
	v_pk_add_f32 v[94:95], v[10:11], v[72:73]
	v_lshlrev_b32_e32 v72, 16, v74
	v_and_b32_e32 v73, 0xffff0000, v74
	v_lshlrev_b32_e32 v74, 16, v75
	v_and_b32_e32 v75, 0xffff0000, v75
	v_pk_add_f32 v[92:93], v[8:9], v[76:77]
	v_pk_add_f32 v[74:75], v[14:15], v[74:75]
	v_pk_add_f32 v[72:73], v[12:13], v[72:73]
	v_cvt_pk_bf16_f32 v76, v92, v93
	v_cvt_pk_bf16_f32 v77, v94, v95
	v_mov_b64_e32 v[146:147], v[94:95]
	v_cvt_pk_bf16_f32 v78, v72, v73
	v_cvt_pk_bf16_f32 v79, v74, v75
	global_store_dwordx4 v[100:101], v[76:79], off offset:1024 nt
	global_load_dwordx4 v[82:85], v[80:81], off offset:2048
	v_mov_b64_e32 v[144:145], v[92:93]
	v_mov_b32_e32 v200, v72
	v_mov_b32_e32 v217, v73
	v_mov_b32_e32 v205, v74
	v_mov_b32_e32 v199, v75
	s_waitcnt vmcnt(0)
	v_lshlrev_b32_e32 v76, 16, v82
	v_and_b32_e32 v77, 0xffff0000, v82
	v_lshlrev_b32_e32 v78, 16, v83
	v_and_b32_e32 v79, 0xffff0000, v83
	v_lshlrev_b32_e32 v82, 16, v84
	v_and_b32_e32 v83, 0xffff0000, v84
	v_lshlrev_b32_e32 v84, 16, v85
	v_and_b32_e32 v85, 0xffff0000, v85
	v_pk_add_f32 v[78:79], v[18:19], v[78:79]
	v_pk_add_f32 v[76:77], v[16:17], v[76:77]
	v_pk_add_f32 v[98:99], v[22:23], v[84:85]
	v_pk_add_f32 v[96:97], v[20:21], v[82:83]
	v_cvt_pk_bf16_f32 v82, v76, v77
	v_cvt_pk_bf16_f32 v83, v78, v79
	v_mov_b32_e32 v175, v79
	v_cvt_pk_bf16_f32 v84, v96, v97
	v_cvt_pk_bf16_f32 v85, v98, v99
	global_store_dwordx4 v[100:101], v[82:85], off offset:2048 nt
	global_load_dwordx4 v[80:83], v[80:81], off offset:3072
	v_mov_b64_e32 v[142:143], v[98:99]
	v_mov_b32_e32 v174, v77
	v_mov_b32_e32 v189, v78
	v_mov_b32_e32 v188, v76
	v_mov_b64_e32 v[140:141], v[96:97]
	s_waitcnt vmcnt(0)
	v_lshlrev_b32_e32 v84, 16, v80
	v_and_b32_e32 v85, 0xffff0000, v80
	v_lshlrev_b32_e32 v80, 16, v81
	v_and_b32_e32 v81, 0xffff0000, v81
	v_pk_add_f32 v[86:87], v[30:31], v[80:81]
	v_lshlrev_b32_e32 v80, 16, v82
	v_and_b32_e32 v81, 0xffff0000, v82
	v_lshlrev_b32_e32 v82, 16, v83
	v_and_b32_e32 v83, 0xffff0000, v83
	v_pk_add_f32 v[84:85], v[28:29], v[84:85]
	v_pk_add_f32 v[82:83], v[26:27], v[82:83]
	v_pk_add_f32 v[80:81], v[24:25], v[80:81]
	v_cvt_pk_bf16_f32 v88, v84, v85
	v_cvt_pk_bf16_f32 v89, v86, v87
	v_mov_b32_e32 v171, v83
	v_cvt_pk_bf16_f32 v90, v80, v81
	v_cvt_pk_bf16_f32 v91, v82, v83
	global_store_dwordx4 v[100:101], v[88:91], off offset:3072 nt
	global_load_dwordx4 v[88:91], v[108:109], off
	v_mov_b32_e32 v170, v81
	v_mov_b32_e32 v173, v82
	v_mov_b32_e32 v172, v80
	v_mov_b32_e32 v204, v84
	v_mov_b32_e32 v229, v85
	v_mov_b32_e32 v228, v86
	v_mov_b32_e32 v227, v87
	s_waitcnt vmcnt(0)
	v_lshlrev_b32_e32 v100, 16, v88
	v_and_b32_e32 v101, 0xffff0000, v88
	v_lshlrev_b32_e32 v88, 16, v89
	v_and_b32_e32 v89, 0xffff0000, v89
	v_pk_add_f32 v[118:119], v[38:39], v[88:89]
	v_lshlrev_b32_e32 v88, 16, v90
	v_and_b32_e32 v89, 0xffff0000, v90
	v_lshlrev_b32_e32 v90, 16, v91
	v_and_b32_e32 v91, 0xffff0000, v91
	v_pk_add_f32 v[116:117], v[36:37], v[100:101]
	v_pk_add_f32 v[90:91], v[54:55], v[90:91]
	v_pk_add_f32 v[88:89], v[52:53], v[88:89]
	v_cvt_pk_bf16_f32 v100, v116, v117
	v_cvt_pk_bf16_f32 v101, v118, v119
	v_mov_b64_e32 v[134:135], v[118:119]
	v_cvt_pk_bf16_f32 v102, v88, v89
	v_cvt_pk_bf16_f32 v103, v90, v91
	global_store_dwordx4 v[128:129], v[100:103], off nt
	global_load_dwordx4 v[102:105], v[108:109], off offset:1024
	v_mov_b64_e32 v[132:133], v[116:117]
	v_mov_b32_e32 v198, v88
	v_mov_b32_e32 v216, v89
	v_mov_b32_e32 v207, v90
	v_mov_b32_e32 v203, v91
	s_waitcnt vmcnt(0)
	v_lshlrev_b32_e32 v100, 16, v102
	v_and_b32_e32 v101, 0xffff0000, v102
	v_lshlrev_b32_e32 v102, 16, v103
	v_and_b32_e32 v103, 0xffff0000, v103
	v_lshlrev_b32_e32 v106, 16, v104
	v_and_b32_e32 v107, 0xffff0000, v104
	v_lshlrev_b32_e32 v104, 16, v105
	v_and_b32_e32 v105, 0xffff0000, v105
	v_pk_add_f32 v[102:103], v[34:35], v[102:103]
	v_pk_add_f32 v[100:101], v[32:33], v[100:101]
	v_pk_add_f32 v[126:127], v[42:43], v[104:105]
	v_pk_add_f32 v[124:125], v[40:41], v[106:107]
	v_cvt_pk_bf16_f32 v104, v100, v101
	v_cvt_pk_bf16_f32 v105, v102, v103
	v_mov_b32_e32 v163, v103
	v_cvt_pk_bf16_f32 v106, v124, v125
	v_cvt_pk_bf16_f32 v107, v126, v127
	global_store_dwordx4 v[128:129], v[104:107], off offset:1024 nt
	global_load_dwordx4 v[110:113], v[108:109], off offset:2048
	v_mov_b32_e32 v162, v101
	v_mov_b32_e32 v165, v102
	v_mov_b32_e32 v164, v100
	s_waitcnt vmcnt(0)
	v_lshlrev_b32_e32 v104, 16, v110
	v_and_b32_e32 v105, 0xffff0000, v110
	v_lshlrev_b32_e32 v106, 16, v111
	v_and_b32_e32 v107, 0xffff0000, v111
	v_lshlrev_b32_e32 v110, 16, v112
	v_and_b32_e32 v111, 0xffff0000, v112
	v_lshlrev_b32_e32 v112, 16, v113
	v_and_b32_e32 v113, 0xffff0000, v113
	v_pk_add_f32 v[106:107], v[66:67], v[106:107]
	v_pk_add_f32 v[104:105], v[64:65], v[104:105]
	v_pk_add_f32 v[114:115], v[58:59], v[112:113]
	v_pk_add_f32 v[112:113], v[56:57], v[110:111]
	v_cvt_pk_bf16_f32 v120, v104, v105
	v_cvt_pk_bf16_f32 v121, v106, v107
	v_mov_b32_e32 v167, v115
	v_cvt_pk_bf16_f32 v122, v112, v113
	v_cvt_pk_bf16_f32 v123, v114, v115
	global_store_dwordx4 v[128:129], v[120:123], off offset:2048 nt
	global_load_dwordx4 v[108:111], v[108:109], off offset:3072
	v_mov_b32_e32 v166, v113
	v_mov_b32_e32 v169, v114
	v_mov_b32_e32 v168, v112
	v_mov_b32_e32 v202, v104
	v_mov_b32_e32 v226, v105
	v_mov_b32_e32 v219, v106
	v_mov_b32_e32 v218, v107
	s_waitcnt vmcnt(0)
	v_lshlrev_b32_e32 v120, 16, v108
	v_and_b32_e32 v121, 0xffff0000, v108
	v_lshlrev_b32_e32 v108, 16, v109
	v_and_b32_e32 v109, 0xffff0000, v109
	v_pk_add_f32 v[138:139], v[62:63], v[108:109]
	v_lshlrev_b32_e32 v108, 16, v110
	v_and_b32_e32 v109, 0xffff0000, v110
	v_lshlrev_b32_e32 v110, 16, v111
	v_and_b32_e32 v111, 0xffff0000, v111
	v_pk_add_f32 v[136:137], v[60:61], v[120:121]
	v_pk_add_f32 v[110:111], v[70:71], v[110:111]
	v_pk_add_f32 v[108:109], v[68:69], v[108:109]
	v_cvt_pk_bf16_f32 v120, v136, v137
	v_cvt_pk_bf16_f32 v121, v138, v139
	v_mov_b32_e32 v230, v110
	v_cvt_pk_bf16_f32 v122, v108, v109
	v_cvt_pk_bf16_f32 v123, v110, v111
	global_store_dwordx4 v[128:129], v[120:123], off offset:3072 nt
	v_mov_b64_e32 v[130:131], v[126:127]
	v_mov_b64_e32 v[128:129], v[124:125]
	v_mov_b64_e32 v[120:121], v[136:137]
	v_mov_b64_e32 v[122:123], v[138:139]
	v_mov_b32_e32 v206, v108
	v_mov_b32_e32 v231, v109
	v_mov_b32_e32 v232, v111
	s_cbranch_execnz .LBB0_287

.LBB0_287:
	v_pk_mul_f32 v[0:1], v[190:191], v[190:191]
	v_pk_mul_f32 v[2:3], v[192:193], v[192:193]
	v_pk_fma_f32 v[0:1], v[194:195], v[194:195], v[0:1]
	v_pk_fma_f32 v[2:3], v[196:197], v[196:197], v[2:3]
	v_pk_add_f32 v[0:1], v[0:1], v[0:1] op_sel_hi:[0,1]
	v_mul_f32_e32 v201, v92, v92
	v_mul_f32_e32 v5, v93, v93
	v_mul_f32_e32 v0, v94, v94
	v_mov_b32_e32 v4, v200
	v_pk_add_f32 v[2:3], v[2:3], v[2:3] op_sel_hi:[0,1]
	v_pk_fma_f32 v[6:7], v[94:95], v[94:95], v[0:1] op_sel_hi:[1,1,0]
	v_pk_add_f32 v[4:5], v[200:201], v[4:5]
	v_mul_f32_e32 v6, v217, v217
	v_mul_f32_e32 v2, v205, v205
	v_mul_f32_e32 v0, v199, v199
	v_mul_f32_e32 v8, v200, v200
	v_mov_b32_e32 v9, v5
	v_pk_add_f32 v[4:5], v[8:9], v[6:7]
	v_pk_add_f32 v[0:1], v[2:3], v[0:1]
	v_pk_mul_f32 v[2:3], v[174:175], v[174:175]
	v_pk_add_f32 v[0:1], v[4:5], v[0:1]
	v_pk_fma_f32 v[2:3], v[188:189], v[188:189], v[2:3]
	v_pk_add_f32 v[0:1], v[0:1], v[0:1] op_sel_hi:[0,1]
	v_mul_f32_e32 v205, v96, v96
	v_mul_f32_e32 v5, v97, v97
	v_mul_f32_e32 v0, v98, v98
	v_mov_b32_e32 v4, v204
	v_pk_add_f32 v[2:3], v[2:3], v[2:3] op_sel_hi:[0,1]
	v_pk_fma_f32 v[6:7], v[98:99], v[98:99], v[0:1] op_sel_hi:[1,1,0]
	v_pk_add_f32 v[4:5], v[204:205], v[4:5]
	v_mul_f32_e32 v6, v229, v229
	v_mul_f32_e32 v2, v228, v228
	v_mul_f32_e32 v0, v227, v227
	v_mul_f32_e32 v8, v204, v204
	v_mov_b32_e32 v9, v5
	v_pk_add_f32 v[4:5], v[8:9], v[6:7]
	v_pk_add_f32 v[0:1], v[2:3], v[0:1]
	v_pk_mul_f32 v[2:3], v[170:171], v[170:171]
	v_pk_add_f32 v[0:1], v[4:5], v[0:1]
	v_pk_fma_f32 v[2:3], v[172:173], v[172:173], v[2:3]
	v_pk_add_f32 v[0:1], v[0:1], v[0:1] op_sel_hi:[0,1]
	v_mul_f32_e32 v199, v116, v116
	v_mul_f32_e32 v5, v117, v117
	v_mul_f32_e32 v0, v118, v118
	v_mov_b32_e32 v4, v198
	v_pk_add_f32 v[2:3], v[2:3], v[2:3] op_sel_hi:[0,1]
	v_pk_fma_f32 v[6:7], v[118:119], v[118:119], v[0:1] op_sel_hi:[1,1,0]
	v_pk_add_f32 v[4:5], v[198:199], v[4:5]
	v_mul_f32_e32 v6, v216, v216
	v_mul_f32_e32 v2, v207, v207
	v_mul_f32_e32 v0, v203, v203
	v_mul_f32_e32 v8, v198, v198
	v_mov_b32_e32 v9, v5
	v_pk_add_f32 v[4:5], v[8:9], v[6:7]
	v_pk_add_f32 v[0:1], v[2:3], v[0:1]
	v_pk_mul_f32 v[2:3], v[162:163], v[162:163]
	v_pk_add_f32 v[0:1], v[4:5], v[0:1]
	v_pk_fma_f32 v[2:3], v[164:165], v[164:165], v[2:3]
	v_pk_add_f32 v[0:1], v[0:1], v[0:1] op_sel_hi:[0,1]
	v_mul_f32_e32 v203, v124, v124
	v_mul_f32_e32 v5, v125, v125
	v_mul_f32_e32 v0, v126, v126
	v_mov_b32_e32 v4, v202
	v_pk_add_f32 v[2:3], v[2:3], v[2:3] op_sel_hi:[0,1]
	v_pk_fma_f32 v[6:7], v[126:127], v[126:127], v[0:1] op_sel_hi:[1,1,0]
	v_pk_add_f32 v[4:5], v[202:203], v[4:5]
	v_mul_f32_e32 v6, v226, v226
	v_mul_f32_e32 v2, v219, v219
	v_mul_f32_e32 v0, v218, v218
	v_mul_f32_e32 v8, v202, v202
	v_mov_b32_e32 v9, v5
	v_pk_add_f32 v[4:5], v[8:9], v[6:7]
	v_pk_add_f32 v[0:1], v[2:3], v[0:1]
	v_pk_mul_f32 v[2:3], v[166:167], v[166:167]
	v_pk_add_f32 v[0:1], v[4:5], v[0:1]
	v_pk_fma_f32 v[2:3], v[168:169], v[168:169], v[2:3]
	v_pk_add_f32 v[0:1], v[0:1], v[0:1] op_sel_hi:[0,1]
	v_mul_f32_e32 v207, v136, v136
	v_mul_f32_e32 v5, v137, v137
	v_mul_f32_e32 v0, v138, v138
	v_mov_b32_e32 v4, v206
	v_pk_add_f32 v[2:3], v[2:3], v[2:3] op_sel_hi:[0,1]
	v_pk_fma_f32 v[6:7], v[138:139], v[138:139], v[0:1] op_sel_hi:[1,1,0]
	v_pk_add_f32 v[4:5], v[206:207], v[4:5]
	v_mul_f32_e32 v6, v231, v231
	v_mul_f32_e32 v2, v230, v230
	v_mul_f32_e32 v0, v232, v232
	v_mul_f32_e32 v8, v206, v206
	v_mov_b32_e32 v9, v5
	v_pk_add_f32 v[4:5], v[8:9], v[6:7]
	v_pk_add_f32 v[0:1], v[2:3], v[0:1]
	s_add_i32 s26, s22, 1
	v_pk_add_f32 v[0:1], v[4:5], v[0:1]
	ds_read_b128 v[2:5], v214
	ds_read_b128 v[6:9], v214 offset:16384
	v_add_f32_e32 v0, v0, v1
	ds_bpermute_b32 v1, v208, v0
	ds_read_b128 v[10:13], v214 offset:1024
	ds_read_b128 v[14:17], v214 offset:17408
	s_ashr_i32 s27, s26, 31
	s_waitcnt lgkmcnt(2)
	v_add_f32_e32 v0, v0, v1
	ds_bpermute_b32 v1, v209, v0
	s_waitcnt lgkmcnt(0)
	v_add_f32_e32 v0, v0, v1
	ds_bpermute_b32 v1, v210, v0
	s_waitcnt lgkmcnt(0)
	v_add_f32_e32 v0, v0, v1
	ds_bpermute_b32 v1, v211, v0
	s_waitcnt lgkmcnt(0)
	v_add_f32_e32 v0, v0, v1
	ds_bpermute_b32 v1, v212, v0
	s_waitcnt lgkmcnt(0)
	v_add_f32_e32 v0, v0, v1
	ds_bpermute_b32 v1, v213, v0
	s_waitcnt lgkmcnt(0)
	v_add_f32_e32 v0, v0, v1
	v_fmamk_f32 v0, v0, 0x39800000, v221
	v_mul_f32_e32 v1, 0x4b800000, v0
	v_cmp_gt_f32_e32 vcc, s42, v0
	s_nop 1
	v_cndmask_b32_e32 v0, v0, v1, vcc
	v_rsq_f32_e32 v0, v0
	s_nop 0
	v_mul_f32_e32 v1, 0x45800000, v0
	v_cndmask_b32_e32 v0, v0, v1, vcc
	v_pk_mul_f32 v[18:19], v[48:49], v[0:1] op_sel_hi:[1,0]
	v_pk_mul_f32 v[20:21], v[50:51], v[0:1] op_sel_hi:[1,0]
	v_pk_fma_f32 v[2:3], v[2:3], v[18:19], v[6:7]
	v_pk_fma_f32 v[4:5], v[4:5], v[20:21], v[8:9]
	v_pk_mul_f32 v[6:7], v[44:45], v[0:1] op_sel_hi:[1,0]
	v_pk_mul_f32 v[8:9], v[46:47], v[0:1] op_sel_hi:[1,0]
	v_lshl_add_u64 v[18:19], s[24:25], 1, v[156:157]
	v_pk_fma_f32 v[8:9], v[12:13], v[8:9], v[16:17]
	v_pk_fma_f32 v[6:7], v[10:11], v[6:7], v[14:15]
	v_cvt_pk_bf16_f32 v2, v2, v3
	v_cvt_pk_bf16_f32 v3, v4, v5
	v_pk_mul_f32 v[20:21], v[144:145], v[0:1] op_sel_hi:[1,0]
	v_cvt_pk_bf16_f32 v4, v6, v7
	v_cvt_pk_bf16_f32 v5, v8, v9
	global_store_dwordx4 v[18:19], v[2:5], off nt
	ds_read_b128 v[2:5], v214 offset:2048
	ds_read_b128 v[6:9], v214 offset:18432
	ds_read_b128 v[10:13], v214 offset:3072
	ds_read_b128 v[14:17], v214 offset:19456
	v_pk_mul_f32 v[22:23], v[146:147], v[0:1] op_sel_hi:[1,0]
	s_lshl_b64 s[24:25], s[26:27], 12
	s_waitcnt lgkmcnt(2)
	v_pk_fma_f32 v[4:5], v[4:5], v[22:23], v[8:9]
	v_pk_fma_f32 v[2:3], v[2:3], v[20:21], v[6:7]
	v_pk_mul_f32 v[6:7], v[72:73], v[0:1] op_sel_hi:[1,0]
	v_pk_mul_f32 v[8:9], v[74:75], v[0:1] op_sel_hi:[1,0]
	s_waitcnt lgkmcnt(0)
	v_pk_fma_f32 v[6:7], v[10:11], v[6:7], v[14:15]
	v_pk_fma_f32 v[8:9], v[12:13], v[8:9], v[16:17]
	v_cvt_pk_bf16_f32 v2, v2, v3
	v_cvt_pk_bf16_f32 v3, v4, v5
	v_cvt_pk_bf16_f32 v4, v6, v7
	v_pk_mul_f32 v[20:21], v[76:77], v[0:1] op_sel_hi:[1,0]
	v_cvt_pk_bf16_f32 v5, v8, v9
	global_store_dwordx4 v[18:19], v[2:5], off offset:1024 nt
	ds_read_b128 v[2:5], v214 offset:4096
	ds_read_b128 v[6:9], v214 offset:20480
	ds_read_b128 v[10:13], v214 offset:5120
	ds_read_b128 v[14:17], v214 offset:21504
	v_pk_mul_f32 v[22:23], v[78:79], v[0:1] op_sel_hi:[1,0]
	s_waitcnt lgkmcnt(2)
	v_pk_fma_f32 v[2:3], v[2:3], v[20:21], v[6:7]
	v_pk_fma_f32 v[4:5], v[4:5], v[22:23], v[8:9]
	v_pk_mul_f32 v[6:7], v[140:141], v[0:1] op_sel_hi:[1,0]
	v_pk_mul_f32 v[8:9], v[142:143], v[0:1] op_sel_hi:[1,0]
	s_waitcnt lgkmcnt(0)
	v_pk_fma_f32 v[6:7], v[10:11], v[6:7], v[14:15]
	v_pk_fma_f32 v[8:9], v[12:13], v[8:9], v[16:17]
	v_cvt_pk_bf16_f32 v2, v2, v3
	v_cvt_pk_bf16_f32 v3, v4, v5
	v_cvt_pk_bf16_f32 v4, v6, v7
	v_pk_mul_f32 v[20:21], v[84:85], v[0:1] op_sel_hi:[1,0]
	v_cvt_pk_bf16_f32 v5, v8, v9
	global_store_dwordx4 v[18:19], v[2:5], off offset:2048 nt
	ds_read_b128 v[2:5], v214 offset:6144
	ds_read_b128 v[6:9], v214 offset:22528
	ds_read_b128 v[10:13], v214 offset:7168
	ds_read_b128 v[14:17], v214 offset:23552
	v_pk_mul_f32 v[22:23], v[86:87], v[0:1] op_sel_hi:[1,0]
	s_waitcnt lgkmcnt(2)
	v_pk_fma_f32 v[2:3], v[20:21], v[2:3], v[6:7]
	v_pk_fma_f32 v[4:5], v[22:23], v[4:5], v[8:9]
	v_pk_mul_f32 v[6:7], v[80:81], v[0:1] op_sel_hi:[1,0]
	v_pk_mul_f32 v[8:9], v[82:83], v[0:1] op_sel_hi:[1,0]
	s_waitcnt lgkmcnt(0)
	v_pk_fma_f32 v[6:7], v[6:7], v[10:11], v[14:15]
	v_pk_fma_f32 v[8:9], v[8:9], v[12:13], v[16:17]
	v_cvt_pk_bf16_f32 v2, v2, v3
	v_cvt_pk_bf16_f32 v3, v4, v5
	v_cvt_pk_bf16_f32 v4, v6, v7
	v_pk_mul_f32 v[20:21], v[132:133], v[0:1] op_sel_hi:[1,0]
	v_cvt_pk_bf16_f32 v5, v8, v9
	global_store_dwordx4 v[18:19], v[2:5], off offset:3072 nt
	ds_read_b128 v[2:5], v214 offset:8192
	ds_read_b128 v[6:9], v214 offset:24576
	ds_read_b128 v[10:13], v214 offset:9216
	ds_read_b128 v[14:17], v214 offset:25600
	v_pk_mul_f32 v[22:23], v[134:135], v[0:1] op_sel_hi:[1,0]
	v_add_co_u32_e32 v18, vcc, s46, v18
	s_waitcnt lgkmcnt(2)
	v_pk_fma_f32 v[4:5], v[22:23], v[4:5], v[8:9]
	v_pk_fma_f32 v[2:3], v[20:21], v[2:3], v[6:7]
	v_pk_mul_f32 v[6:7], v[88:89], v[0:1] op_sel_hi:[1,0]
	v_pk_mul_f32 v[8:9], v[90:91], v[0:1] op_sel_hi:[1,0]
	v_addc_co_u32_e32 v19, vcc, 0, v19, vcc
	s_waitcnt lgkmcnt(0)
	v_pk_fma_f32 v[8:9], v[8:9], v[12:13], v[16:17]
	v_pk_fma_f32 v[6:7], v[6:7], v[10:11], v[14:15]
	v_cvt_pk_bf16_f32 v2, v2, v3
	v_cvt_pk_bf16_f32 v3, v4, v5
	v_pk_mul_f32 v[20:21], v[100:101], v[0:1] op_sel_hi:[1,0]
	v_cvt_pk_bf16_f32 v4, v6, v7
	v_cvt_pk_bf16_f32 v5, v8, v9
	global_store_dwordx4 v[18:19], v[2:5], off nt
	ds_read_b128 v[2:5], v214 offset:10240
	ds_read_b128 v[6:9], v214 offset:26624
	ds_read_b128 v[10:13], v214 offset:11264
	ds_read_b128 v[14:17], v214 offset:27648
	v_pk_mul_f32 v[22:23], v[102:103], v[0:1] op_sel_hi:[1,0]
	s_and_b64 vcc, exec, s[4:5]
	s_mov_b64 s[4:5], -1
	s_waitcnt lgkmcnt(2)
	v_pk_fma_f32 v[4:5], v[22:23], v[4:5], v[8:9]
	v_pk_fma_f32 v[2:3], v[20:21], v[2:3], v[6:7]
	v_pk_mul_f32 v[6:7], v[128:129], v[0:1] op_sel_hi:[1,0]
	v_pk_mul_f32 v[8:9], v[130:131], v[0:1] op_sel_hi:[1,0]
	s_waitcnt lgkmcnt(0)
	v_pk_fma_f32 v[6:7], v[6:7], v[10:11], v[14:15]
	v_pk_fma_f32 v[8:9], v[8:9], v[12:13], v[16:17]
	v_cvt_pk_bf16_f32 v2, v2, v3
	v_cvt_pk_bf16_f32 v3, v4, v5
	v_cvt_pk_bf16_f32 v4, v6, v7
	v_pk_mul_f32 v[20:21], v[104:105], v[0:1] op_sel_hi:[1,0]
	v_cvt_pk_bf16_f32 v5, v8, v9
	global_store_dwordx4 v[18:19], v[2:5], off offset:1024 nt
	ds_read_b128 v[2:5], v214 offset:12288
	ds_read_b128 v[6:9], v214 offset:28672
	ds_read_b128 v[10:13], v214 offset:13312
	ds_read_b128 v[14:17], v214 offset:29696
	v_pk_mul_f32 v[22:23], v[106:107], v[0:1] op_sel_hi:[1,0]
	s_waitcnt lgkmcnt(2)
	v_pk_fma_f32 v[2:3], v[20:21], v[2:3], v[6:7]
	v_pk_fma_f32 v[4:5], v[22:23], v[4:5], v[8:9]
	v_pk_mul_f32 v[6:7], v[112:113], v[0:1] op_sel_hi:[1,0]
	v_pk_mul_f32 v[8:9], v[114:115], v[0:1] op_sel_hi:[1,0]
	s_waitcnt lgkmcnt(0)
	v_pk_fma_f32 v[6:7], v[6:7], v[10:11], v[14:15]
	v_pk_fma_f32 v[8:9], v[8:9], v[12:13], v[16:17]
	v_cvt_pk_bf16_f32 v2, v2, v3
	v_cvt_pk_bf16_f32 v3, v4, v5
	v_cvt_pk_bf16_f32 v4, v6, v7
	v_pk_mul_f32 v[20:21], v[120:121], v[0:1] op_sel_hi:[1,0]
	v_cvt_pk_bf16_f32 v5, v8, v9
	global_store_dwordx4 v[18:19], v[2:5], off offset:2048 nt
	ds_read_b128 v[2:5], v214 offset:14336
	ds_read_b128 v[6:9], v214 offset:30720
	ds_read_b128 v[10:13], v214 offset:15360
	ds_read_b128 v[14:17], v214 offset:31744
	v_pk_mul_f32 v[22:23], v[122:123], v[0:1] op_sel_hi:[1,0]
	s_waitcnt lgkmcnt(2)
	v_pk_fma_f32 v[2:3], v[20:21], v[2:3], v[6:7]
	v_pk_mul_f32 v[6:7], v[108:109], v[0:1] op_sel_hi:[1,0]
	v_pk_mul_f32 v[0:1], v[110:111], v[0:1] op_sel_hi:[1,0]
	v_pk_fma_f32 v[4:5], v[22:23], v[4:5], v[8:9]
	s_waitcnt lgkmcnt(0)
	v_pk_fma_f32 v[8:9], v[0:1], v[12:13], v[16:17]
	v_pk_fma_f32 v[6:7], v[6:7], v[10:11], v[14:15]
	v_cvt_pk_bf16_f32 v0, v2, v3
	v_cvt_pk_bf16_f32 v1, v4, v5
	s_nop 0
	v_cvt_pk_bf16_f32 v2, v6, v7
	v_cvt_pk_bf16_f32 v3, v8, v9
	global_store_dwordx4 v[18:19], v[0:3], off offset:3072 nt
	s_cbranch_vccnz .LBB0_298
	s_nop 0
	v_lshl_add_u64 v[0:1], s[24:25], 1, v[154:155]
	global_load_dwordx4 v[4:7], v[0:1], off
	global_load_dwordx4 v[12:15], v[0:1], off offset:1024
	global_load_dwordx4 v[20:23], v[0:1], off offset:2048
	global_load_dwordx4 v[24:27], v[0:1], off offset:3072
	v_add_co_u32_e32 v0, vcc, s46, v0
	s_nop 1
	v_addc_co_u32_e32 v1, vcc, 0, v1, vcc
	global_load_dwordx4 v[32:35], v[0:1], off
	global_load_dwordx4 v[48:51], v[0:1], off offset:1024
	global_load_dwordx4 v[56:59], v[0:1], off offset:2048
	global_load_dwordx4 v[68:71], v[0:1], off offset:3072
	s_waitcnt vmcnt(7)
	v_lshlrev_b32_e32 v0, 16, v4
	v_and_b32_e32 v1, 0xffff0000, v4
	v_lshlrev_b32_e32 v2, 16, v5
	v_and_b32_e32 v3, 0xffff0000, v5
	v_lshlrev_b32_e32 v4, 16, v6
	v_and_b32_e32 v5, 0xffff0000, v6
	v_lshlrev_b32_e32 v6, 16, v7
	v_and_b32_e32 v7, 0xffff0000, v7
	s_waitcnt vmcnt(6)
	v_lshlrev_b32_e32 v8, 16, v12
	v_and_b32_e32 v9, 0xffff0000, v12
	v_lshlrev_b32_e32 v10, 16, v13
	v_and_b32_e32 v11, 0xffff0000, v13
	v_lshlrev_b32_e32 v12, 16, v14
	v_and_b32_e32 v13, 0xffff0000, v14
	v_lshlrev_b32_e32 v14, 16, v15
	v_and_b32_e32 v15, 0xffff0000, v15
	s_waitcnt vmcnt(5)
	v_lshlrev_b32_e32 v16, 16, v20
	v_and_b32_e32 v17, 0xffff0000, v20
	v_lshlrev_b32_e32 v18, 16, v21
	v_and_b32_e32 v19, 0xffff0000, v21
	v_lshlrev_b32_e32 v20, 16, v22
	v_and_b32_e32 v21, 0xffff0000, v22
	v_lshlrev_b32_e32 v22, 16, v23
	v_and_b32_e32 v23, 0xffff0000, v23
	s_waitcnt vmcnt(4)
	v_lshlrev_b32_e32 v36, 16, v24
	v_and_b32_e32 v37, 0xffff0000, v24
	v_lshlrev_b32_e32 v38, 16, v25
	v_and_b32_e32 v39, 0xffff0000, v25
	v_lshlrev_b32_e32 v28, 16, v26
	v_and_b32_e32 v29, 0xffff0000, v26
	v_lshlrev_b32_e32 v30, 16, v27
	v_and_b32_e32 v31, 0xffff0000, v27
	s_waitcnt vmcnt(3)
	v_lshlrev_b32_e32 v44, 16, v32
	v_and_b32_e32 v45, 0xffff0000, v32
	v_lshlrev_b32_e32 v46, 16, v33
	v_and_b32_e32 v47, 0xffff0000, v33
	v_lshlrev_b32_e32 v52, 16, v34
	v_and_b32_e32 v53, 0xffff0000, v34
	v_lshlrev_b32_e32 v54, 16, v35
	v_and_b32_e32 v55, 0xffff0000, v35
	s_waitcnt vmcnt(2)
	v_lshlrev_b32_e32 v40, 16, v48
	v_and_b32_e32 v41, 0xffff0000, v48
	v_lshlrev_b32_e32 v42, 16, v49
	v_and_b32_e32 v43, 0xffff0000, v49
	v_lshlrev_b32_e32 v48, 16, v50
	v_and_b32_e32 v49, 0xffff0000, v50
	v_lshlrev_b32_e32 v50, 16, v51
	v_and_b32_e32 v51, 0xffff0000, v51
	s_waitcnt vmcnt(1)
	v_lshlrev_b32_e32 v64, 16, v56
	v_and_b32_e32 v65, 0xffff0000, v56
	v_lshlrev_b32_e32 v66, 16, v57
	v_and_b32_e32 v67, 0xffff0000, v57
	v_lshlrev_b32_e32 v56, 16, v58
	v_and_b32_e32 v57, 0xffff0000, v58
	v_lshlrev_b32_e32 v58, 16, v59
	v_and_b32_e32 v59, 0xffff0000, v59
	s_waitcnt vmcnt(0)
	v_lshlrev_b32_e32 v60, 16, v68
	v_and_b32_e32 v61, 0xffff0000, v68
	v_lshlrev_b32_e32 v62, 16, v69
	v_and_b32_e32 v63, 0xffff0000, v69
	v_lshlrev_b32_e32 v68, 16, v70
	v_and_b32_e32 v69, 0xffff0000, v70
	v_lshlrev_b32_e32 v70, 16, v71
	v_and_b32_e32 v71, 0xffff0000, v71
	s_cbranch_execz .LBB0_299

.LBB0_290:
	s_lshl_b64 s[10:11], s[24:25], 1
	s_add_u32 s4, s35, s10
	s_addc_u32 s5, s48, s11
	s_add_u32 s22, s49, s10
	s_addc_u32 s23, s50, s11
	v_lshl_add_u64 v[80:81], s[22:23], 0, v[176:177]
	global_load_dwordx4 v[24:27], v[80:81], off
	v_lshl_add_u64 v[96:97], s[4:5], 0, v[176:177]
	v_lshl_add_u64 v[108:109], s[22:23], 0, v[152:153]
	v_lshl_add_u64 v[124:125], s[4:5], 0, v[152:153]
	s_waitcnt vmcnt(0)
	v_lshlrev_b32_e32 v32, 16, v24
	v_and_b32_e32 v33, 0xffff0000, v24
	v_lshlrev_b32_e32 v24, 16, v25
	v_and_b32_e32 v25, 0xffff0000, v25
	v_pk_add_f32 v[34:35], v[2:3], v[24:25]
	v_lshlrev_b32_e32 v24, 16, v26
	v_and_b32_e32 v25, 0xffff0000, v26
	v_lshlrev_b32_e32 v26, 16, v27
	v_and_b32_e32 v27, 0xffff0000, v27
	v_pk_add_f32 v[32:33], v[0:1], v[32:33]
	v_pk_add_f32 v[26:27], v[6:7], v[26:27]
	v_pk_add_f32 v[24:25], v[4:5], v[24:25]
	v_cvt_pk_bf16_f32 v72, v32, v33
	v_cvt_pk_bf16_f32 v73, v34, v35
	v_mov_b32_e32 v191, v35
	v_cvt_pk_bf16_f32 v74, v24, v25
	v_cvt_pk_bf16_f32 v75, v26, v27
	global_store_dwordx4 v[96:97], v[72:75], off nt
	global_load_dwordx4 v[72:75], v[80:81], off offset:1024
	v_mov_b32_e32 v190, v33
	v_mov_b32_e32 v195, v34
	v_mov_b32_e32 v194, v32
	v_mov_b32_e32 v193, v27
	v_mov_b32_e32 v192, v25
	v_mov_b32_e32 v197, v26
	v_mov_b32_e32 v196, v24
	s_waitcnt vmcnt(0)
	v_lshlrev_b32_e32 v76, 16, v72
	v_and_b32_e32 v77, 0xffff0000, v72
	v_lshlrev_b32_e32 v72, 16, v73
	v_and_b32_e32 v73, 0xffff0000, v73
	v_pk_add_f32 v[94:95], v[10:11], v[72:73]
	v_lshlrev_b32_e32 v72, 16, v74
	v_and_b32_e32 v73, 0xffff0000, v74
	v_lshlrev_b32_e32 v74, 16, v75
	v_and_b32_e32 v75, 0xffff0000, v75
	v_pk_add_f32 v[92:93], v[8:9], v[76:77]
	v_pk_add_f32 v[74:75], v[14:15], v[74:75]
	v_pk_add_f32 v[72:73], v[12:13], v[72:73]
	v_cvt_pk_bf16_f32 v76, v92, v93
	v_cvt_pk_bf16_f32 v77, v94, v95
	v_mov_b64_e32 v[146:147], v[94:95]
	v_cvt_pk_bf16_f32 v78, v72, v73
	v_cvt_pk_bf16_f32 v79, v74, v75
	global_store_dwordx4 v[96:97], v[76:79], off offset:1024 nt
	global_load_dwordx4 v[82:85], v[80:81], off offset:2048
	v_mov_b64_e32 v[144:145], v[92:93]
	v_mov_b32_e32 v200, v72
	v_mov_b32_e32 v217, v73
	v_mov_b32_e32 v205, v74
	v_mov_b32_e32 v199, v75
	s_waitcnt vmcnt(0)
	v_lshlrev_b32_e32 v76, 16, v82
	v_and_b32_e32 v77, 0xffff0000, v82
	v_lshlrev_b32_e32 v78, 16, v83
	v_and_b32_e32 v79, 0xffff0000, v83
	v_lshlrev_b32_e32 v82, 16, v84
	v_and_b32_e32 v83, 0xffff0000, v84
	v_lshlrev_b32_e32 v84, 16, v85
	v_and_b32_e32 v85, 0xffff0000, v85
	v_pk_add_f32 v[78:79], v[18:19], v[78:79]
	v_pk_add_f32 v[76:77], v[16:17], v[76:77]
	v_pk_add_f32 v[106:107], v[22:23], v[84:85]
	v_pk_add_f32 v[104:105], v[20:21], v[82:83]
	v_cvt_pk_bf16_f32 v82, v76, v77
	v_cvt_pk_bf16_f32 v83, v78, v79
	v_mov_b32_e32 v175, v79
	v_cvt_pk_bf16_f32 v84, v104, v105
	v_cvt_pk_bf16_f32 v85, v106, v107
	global_store_dwordx4 v[96:97], v[82:85], off offset:2048 nt
	global_load_dwordx4 v[80:83], v[80:81], off offset:3072
	v_mov_b64_e32 v[142:143], v[106:107]
	v_mov_b32_e32 v174, v77
	v_mov_b32_e32 v189, v78
	v_mov_b32_e32 v188, v76
	v_mov_b64_e32 v[140:141], v[104:105]
	s_waitcnt vmcnt(0)
	v_lshlrev_b32_e32 v84, 16, v80
	v_and_b32_e32 v85, 0xffff0000, v80
	v_lshlrev_b32_e32 v80, 16, v81
	v_and_b32_e32 v81, 0xffff0000, v81
	v_pk_add_f32 v[86:87], v[38:39], v[80:81]
	v_lshlrev_b32_e32 v80, 16, v82
	v_and_b32_e32 v81, 0xffff0000, v82
	v_lshlrev_b32_e32 v82, 16, v83
	v_and_b32_e32 v83, 0xffff0000, v83
	v_pk_add_f32 v[84:85], v[36:37], v[84:85]
	v_pk_add_f32 v[82:83], v[30:31], v[82:83]
	v_pk_add_f32 v[80:81], v[28:29], v[80:81]
	v_cvt_pk_bf16_f32 v88, v84, v85
	v_cvt_pk_bf16_f32 v89, v86, v87
	v_mov_b32_e32 v171, v83
	v_cvt_pk_bf16_f32 v90, v80, v81
	v_cvt_pk_bf16_f32 v91, v82, v83
	global_store_dwordx4 v[96:97], v[88:91], off offset:3072 nt
	global_load_dwordx4 v[88:91], v[108:109], off
	v_mov_b32_e32 v170, v81
	v_mov_b32_e32 v173, v82
	v_mov_b32_e32 v172, v80
	v_mov_b32_e32 v204, v84
	v_mov_b32_e32 v229, v85
	v_mov_b32_e32 v228, v86
	v_mov_b32_e32 v227, v87
	s_waitcnt vmcnt(0)
	v_lshlrev_b32_e32 v96, 16, v88
	v_and_b32_e32 v97, 0xffff0000, v88
	v_lshlrev_b32_e32 v88, 16, v89
	v_and_b32_e32 v89, 0xffff0000, v89
	v_pk_add_f32 v[118:119], v[46:47], v[88:89]
	v_lshlrev_b32_e32 v88, 16, v90
	v_and_b32_e32 v89, 0xffff0000, v90
	v_lshlrev_b32_e32 v90, 16, v91
	v_and_b32_e32 v91, 0xffff0000, v91
	v_pk_add_f32 v[116:117], v[44:45], v[96:97]
	v_pk_add_f32 v[90:91], v[54:55], v[90:91]
	v_pk_add_f32 v[88:89], v[52:53], v[88:89]
	v_cvt_pk_bf16_f32 v96, v116, v117
	v_cvt_pk_bf16_f32 v97, v118, v119
	v_mov_b64_e32 v[134:135], v[118:119]
	v_cvt_pk_bf16_f32 v98, v88, v89
	v_cvt_pk_bf16_f32 v99, v90, v91
	global_store_dwordx4 v[124:125], v[96:99], off nt
	global_load_dwordx4 v[98:101], v[108:109], off offset:1024
	v_mov_b64_e32 v[132:133], v[116:117]
	v_mov_b32_e32 v198, v88
	v_mov_b32_e32 v216, v89
	v_mov_b32_e32 v207, v90
	v_mov_b32_e32 v203, v91
	s_waitcnt vmcnt(0)
	v_lshlrev_b32_e32 v96, 16, v98
	v_and_b32_e32 v97, 0xffff0000, v98
	v_lshlrev_b32_e32 v98, 16, v99
	v_and_b32_e32 v99, 0xffff0000, v99
	v_lshlrev_b32_e32 v102, 16, v100
	v_and_b32_e32 v103, 0xffff0000, v100
	v_lshlrev_b32_e32 v100, 16, v101
	v_and_b32_e32 v101, 0xffff0000, v101
	v_pk_add_f32 v[98:99], v[42:43], v[98:99]
	v_pk_add_f32 v[96:97], v[40:41], v[96:97]
	v_pk_add_f32 v[130:131], v[50:51], v[100:101]
	v_pk_add_f32 v[128:129], v[48:49], v[102:103]
	v_cvt_pk_bf16_f32 v100, v96, v97
	v_cvt_pk_bf16_f32 v101, v98, v99
	v_mov_b32_e32 v163, v99
	v_cvt_pk_bf16_f32 v102, v128, v129
	v_cvt_pk_bf16_f32 v103, v130, v131
	global_store_dwordx4 v[124:125], v[100:103], off offset:1024 nt
	global_load_dwordx4 v[110:113], v[108:109], off offset:2048
	v_mov_b32_e32 v162, v97
	v_mov_b32_e32 v165, v98
	v_mov_b32_e32 v164, v96
	s_waitcnt vmcnt(0)
	v_lshlrev_b32_e32 v100, 16, v110
	v_and_b32_e32 v101, 0xffff0000, v110
	v_lshlrev_b32_e32 v102, 16, v111
	v_and_b32_e32 v103, 0xffff0000, v111
	v_lshlrev_b32_e32 v110, 16, v112
	v_and_b32_e32 v111, 0xffff0000, v112
	v_lshlrev_b32_e32 v112, 16, v113
	v_and_b32_e32 v113, 0xffff0000, v113
	v_pk_add_f32 v[102:103], v[66:67], v[102:103]
	v_pk_add_f32 v[100:101], v[64:65], v[100:101]
	v_pk_add_f32 v[114:115], v[58:59], v[112:113]
	v_pk_add_f32 v[112:113], v[56:57], v[110:111]
	v_cvt_pk_bf16_f32 v120, v100, v101
	v_cvt_pk_bf16_f32 v121, v102, v103
	v_mov_b32_e32 v167, v115
	v_cvt_pk_bf16_f32 v122, v112, v113
	v_cvt_pk_bf16_f32 v123, v114, v115
	global_store_dwordx4 v[124:125], v[120:123], off offset:2048 nt
	global_load_dwordx4 v[108:111], v[108:109], off offset:3072
	v_mov_b32_e32 v166, v113
	v_mov_b32_e32 v169, v114
	v_mov_b32_e32 v168, v112
	v_mov_b32_e32 v202, v100
	v_mov_b32_e32 v226, v101
	v_mov_b32_e32 v219, v102
	v_mov_b32_e32 v218, v103
	s_waitcnt vmcnt(0)
	v_lshlrev_b32_e32 v120, 16, v108
	v_and_b32_e32 v121, 0xffff0000, v108
	v_lshlrev_b32_e32 v108, 16, v109
	v_and_b32_e32 v109, 0xffff0000, v109
	v_pk_add_f32 v[138:139], v[62:63], v[108:109]
	v_lshlrev_b32_e32 v108, 16, v110
	v_and_b32_e32 v109, 0xffff0000, v110
	v_lshlrev_b32_e32 v110, 16, v111
	v_and_b32_e32 v111, 0xffff0000, v111
	v_pk_add_f32 v[136:137], v[60:61], v[120:121]
	v_pk_add_f32 v[110:111], v[70:71], v[110:111]
	v_pk_add_f32 v[108:109], v[68:69], v[108:109]
	v_cvt_pk_bf16_f32 v120, v136, v137
	v_cvt_pk_bf16_f32 v121, v138, v139
	v_mov_b32_e32 v230, v110
	v_cvt_pk_bf16_f32 v122, v108, v109
	v_cvt_pk_bf16_f32 v123, v110, v111
	global_store_dwordx4 v[124:125], v[120:123], off offset:3072 nt
	v_mov_b64_e32 v[124:125], v[128:129]
	v_mov_b64_e32 v[126:127], v[130:131]
	v_mov_b64_e32 v[120:121], v[136:137]
	v_mov_b64_e32 v[122:123], v[138:139]
	v_mov_b32_e32 v206, v108
	v_mov_b32_e32 v231, v109
	v_mov_b32_e32 v232, v111
	s_cbranch_execnz .LBB0_281
	s_branch .LBB0_280

.LBB0_541:
	s_lshl_b64 s[2:3], s[24:25], 10
	v_cvt_pk_bf16_f32 v12, v20, v21
	v_cvt_pk_bf16_f32 v13, v22, v23
	v_lshl_add_u64 v[16:17], v[48:49], 0, s[2:3]
	s_add_i32 s10, s10, s11
	s_add_i32 s36, s36, s43
	s_add_i32 s22, s22, s44
	v_cvt_pk_bf16_f32 v14, v24, v25
	v_cvt_pk_bf16_f32 v15, v26, v27
	global_store_dwordx4 v[16:17], v[12:15], off nt
	s_cmpk_lt_i32 s10, 0x1000
	s_nop 0
	v_lshl_add_u64 v[12:13], v[50:51], 0, s[2:3]
	global_store_dwordx4 v[12:13], v[8:11], off nt
	s_cbranch_scc0 .LBB0_558

.LBB0_544:
	s_ashr_i32 s2, s10, 4
	s_and_b32 s2, s2, -4
	s_or_b32 s2, s2, s92
	s_ashr_i32 s3, s2, 31
	s_lshl_b64 s[2:3], s[2:3], 17
	v_mov_b32_e32 v53, s3
	s_andn2_b64 vcc, exec, s[8:9]
	v_or_b32_e32 v65, s2, v44
	s_cbranch_vccnz .LBB0_546
	s_load_dwordx2 s[2:3], s[20:21], 0xe0
	s_and_b32 s8, s36, 0x1f800
	v_or_b32_e32 v52, s8, v65
	s_waitcnt lgkmcnt(0)
	v_lshl_add_u64 v[58:59], v[52:53], 2, s[2:3]
	s_mov_b64 s[2:3], 0x10000000
	v_lshl_add_u64 v[54:55], v[58:59], 0, s[2:3]
	s_brev_b32 s2, 8
	v_add_co_u32_e32 v56, vcc, s2, v58
	s_mov_b64 s[2:3], 0x14000000
	s_nop 0
	v_addc_co_u32_e32 v57, vcc, 0, v59, vcc
	v_lshl_add_u64 v[60:61], v[58:59], 0, s[2:3]
	v_add_co_u32_e32 v58, vcc, 0x14000000, v58
	global_store_dwordx4 v[56:57], v[40:43], off nt
	global_store_dwordx4 v[54:55], v[36:39], off offset:16 nt
	v_lshlrev_b32_e32 v54, 16, v32
	v_and_b32_e32 v55, 0xffff0000, v32
	v_lshlrev_b32_e32 v56, 16, v33
	v_and_b32_e32 v57, 0xffff0000, v33
	v_addc_co_u32_e32 v59, vcc, 0, v59, vcc
	global_store_dwordx4 v[58:59], v[54:57], off nt
	v_mov_b32_e32 v58, v36
	v_mov_b32_e32 v59, v37
	v_lshlrev_b32_e32 v54, 16, v34
	v_and_b32_e32 v55, 0xffff0000, v34
	v_lshlrev_b32_e32 v56, 16, v35
	v_and_b32_e32 v57, 0xffff0000, v35
	global_store_dwordx4 v[60:61], v[54:57], off offset:16 nt
	v_mov_b32_e32 v60, v38
	v_mov_b32_e32 v61, v39
	v_mov_b32_e32 v54, v40
	v_mov_b32_e32 v55, v41
	v_mov_b32_e32 v56, v42
	v_mov_b32_e32 v57, v43
.LBB0_546:
	s_lshl_b64 s[2:3], s[22:23], 10
	v_cvt_pk_bf16_f32 v36, v54, v55
	v_cvt_pk_bf16_f32 v37, v56, v57
	v_cvt_pk_bf16_f32 v38, v58, v59
	v_cvt_pk_bf16_f32 v39, v60, v61
	v_lshl_add_u64 v[40:41], v[48:49], 0, s[2:3]
	global_store_dwordx4 v[40:41], v[36:39], off nt
	v_lshlrev_b32_e32 v42, 16, v29
	v_and_b32_e32 v43, 0xffff0000, v29
	v_lshlrev_b32_e32 v38, 16, v28
	v_and_b32_e32 v39, 0xffff0000, v28
	v_pk_mul_f32 v[40:41], v[38:39], v[38:39]
	v_lshl_add_u64 v[36:37], v[50:51], 0, s[2:3]
	v_pk_mul_f32 v[28:29], v[42:43], v[42:43]
	v_add_f32_e32 v40, v40, v41
	global_store_dwordx4 v[36:37], v[32:35], off nt
	v_add_f32_e32 v28, v28, v40
	v_add_f32_e32 v28, v29, v28
	v_lshlrev_b32_e32 v34, 16, v30
	v_and_b32_e32 v35, 0xffff0000, v30
	v_pk_mul_f32 v[32:33], v[34:35], v[34:35]
	v_lshlrev_b32_e32 v30, 16, v31
	v_and_b32_e32 v31, 0xffff0000, v31
	v_add_f32_e32 v28, v32, v28
	v_pk_mul_f32 v[36:37], v[30:31], v[30:31]
	v_add_f32_e32 v28, v33, v28
	v_add_f32_e32 v28, v36, v28
	v_add_f32_e32 v28, v37, v28
	ds_bpermute_b32 v29, v45, v28
	s_ashr_i32 s29, s28, 31
	s_mov_b64 s[34:35], -1
	s_waitcnt lgkmcnt(0)
	v_add_f32_e32 v28, v28, v29
	ds_bpermute_b32 v29, v62, v28
	s_waitcnt lgkmcnt(0)
	v_add_f32_e32 v28, v28, v29
	ds_bpermute_b32 v29, v63, v28
	s_waitcnt lgkmcnt(0)
	v_add_f32_e32 v28, v28, v29
	ds_bpermute_b32 v29, v64, v28
	s_waitcnt lgkmcnt(0)
	v_add_f32_e32 v28, v28, v29
	v_fmamk_f32 v28, v28, 0x3c000000, v221
	v_cmp_gt_f32_e32 vcc, s42, v28
	v_mul_f32_e32 v29, 0x4b800000, v28
	s_nop 0
	v_cndmask_b32_e32 v28, v28, v29, vcc
	v_rsq_f32_e32 v28, v28
	s_nop 0
	v_mul_f32_e32 v29, 0x45800000, v28
	v_cndmask_b32_e32 v36, v28, v29, vcc
	v_pk_mul_f32 v[28:29], v[0:1], v[36:37] op_sel_hi:[1,0]
	v_pk_mul_f32 v[40:41], v[4:5], v[36:37] op_sel_hi:[1,0]
	v_pk_mul_f32 v[32:33], v[28:29], v[38:39]
	v_pk_mul_f32 v[28:29], v[40:41], v[34:35]
	v_pk_mul_f32 v[34:35], v[2:3], v[36:37] op_sel_hi:[1,0]
	v_pk_mul_f32 v[36:37], v[6:7], v[36:37] op_sel_hi:[1,0]
	v_pk_mul_f32 v[34:35], v[34:35], v[42:43]
	v_pk_mul_f32 v[30:31], v[36:37], v[30:31]
	v_cndmask_b32_e64 v36, 0, 1, s[30:31]
	v_cmp_ne_u32_e64 s[8:9], 1, v36
	s_andn2_b64 vcc, exec, s[30:31]
	s_cbranch_vccnz .LBB0_548
	v_mov_b32_e32 v36, s28
	v_mov_b32_e32 v37, s37
	v_cndmask_b32_e64 v36, v36, v37, s[4:5]
	v_lshlrev_b32_e32 v36, 8, v36
	v_and_b32_e32 v176, 0x3f00, v36
	v_lshl_add_u64 v[36:37], v[46:47], 0, v[176:177]
	global_load_dwordx4 v[54:57], v[36:37], off offset:48
	global_load_dwordx4 v[40:43], v[36:37], off offset:32
	global_load_dwordx4 v[58:61], v[36:37], off offset:16
	s_nop 0
	global_load_dwordx4 v[36:39], v[36:37], off
	ds_bpermute_b32 v66, v63, v32
	ds_bpermute_b32 v67, v63, v33
	s_mov_b64 s[34:35], 0
	s_waitcnt vmcnt(0)
	v_mov_b32_e32 v69, v38
	v_mov_b32_e32 v38, v37
	v_mov_b32_e32 v68, v36
	s_waitcnt lgkmcnt(0)
	v_pk_mul_f32 v[36:37], v[38:39], v[66:67]
	ds_bpermute_b32 v38, v63, v34
	ds_bpermute_b32 v39, v63, v35
	v_mov_b32_e32 v66, v58
	v_mov_b32_e32 v67, v60
	v_mov_b32_e32 v60, v59
	ds_bpermute_b32 v58, v63, v28
	ds_bpermute_b32 v59, v63, v29
	s_waitcnt lgkmcnt(2)
	v_pk_mul_f32 v[38:39], v[60:61], v[38:39]
	v_mov_b32_e32 v61, v42
	v_mov_b32_e32 v42, v41
	v_mov_b32_e32 v60, v40
	s_waitcnt lgkmcnt(0)
	v_pk_mul_f32 v[40:41], v[42:43], v[58:59]
	ds_bpermute_b32 v42, v63, v30
	ds_bpermute_b32 v43, v63, v31
	v_mov_b32_e32 v59, v56
	v_mov_b32_e32 v56, v55
	v_cndmask_b32_e64 v37, v37, -v37, s[6:7]
	v_cndmask_b32_e64 v36, v36, -v36, s[6:7]
	s_waitcnt lgkmcnt(0)
	v_pk_mul_f32 v[42:43], v[56:57], v[42:43]
	v_cndmask_b32_e64 v39, v39, -v39, s[6:7]
	v_cndmask_b32_e64 v38, v38, -v38, s[6:7]
	v_cndmask_b32_e64 v41, v41, -v41, s[6:7]
	v_cndmask_b32_e64 v40, v40, -v40, s[6:7]
	v_mov_b32_e32 v58, v54
	v_cndmask_b32_e64 v43, v43, -v43, s[6:7]
	v_cndmask_b32_e64 v42, v42, -v42, s[6:7]
	v_pk_fma_f32 v[36:37], v[32:33], v[68:69], v[36:37]
	v_pk_fma_f32 v[38:39], v[34:35], v[66:67], v[38:39]
	v_pk_fma_f32 v[40:41], v[28:29], v[60:61], v[40:41]
	v_pk_fma_f32 v[42:43], v[30:31], v[58:59], v[42:43]
.LBB0_548:
	s_andn2_b64 vcc, exec, s[34:35]
	s_cbranch_vccnz .LBB0_550
	s_load_dwordx2 s[2:3], s[20:21], 0xe0
	s_add_i32 s23, s36, 0x200
	s_and_b32 s23, s23, 0x1fa00
	v_or_b32_e32 v52, s23, v65
	s_waitcnt lgkmcnt(0)
	v_lshl_add_u64 v[40:41], v[52:53], 2, s[2:3]
	s_mov_b64 s[2:3], 0x10000000
	v_lshl_add_u64 v[36:37], v[40:41], 0, s[2:3]
	s_brev_b32 s2, 8
	v_add_co_u32_e32 v38, vcc, s2, v40
	s_mov_b64 s[2:3], 0x14000000
	s_nop 0
	v_addc_co_u32_e32 v39, vcc, 0, v41, vcc
	v_lshl_add_u64 v[42:43], v[40:41], 0, s[2:3]
	v_add_co_u32_e32 v40, vcc, 0x14000000, v40
	global_store_dwordx4 v[38:39], v[32:35], off nt
	global_store_dwordx4 v[36:37], v[28:31], off offset:16 nt
	v_lshlrev_b32_e32 v36, 16, v24
	v_and_b32_e32 v37, 0xffff0000, v24
	v_lshlrev_b32_e32 v38, 16, v25
	v_and_b32_e32 v39, 0xffff0000, v25
	v_addc_co_u32_e32 v41, vcc, 0, v41, vcc
	global_store_dwordx4 v[40:41], v[36:39], off nt
	v_mov_b32_e32 v40, v28
	v_mov_b32_e32 v41, v29
	v_lshlrev_b32_e32 v36, 16, v26
	v_and_b32_e32 v37, 0xffff0000, v26
	v_lshlrev_b32_e32 v38, 16, v27
	v_and_b32_e32 v39, 0xffff0000, v27
	global_store_dwordx4 v[42:43], v[36:39], off offset:16 nt
	v_mov_b32_e32 v42, v30
	v_mov_b32_e32 v43, v31
	v_mov_b32_e32 v36, v32
	v_mov_b32_e32 v37, v33
	v_mov_b32_e32 v38, v34
	v_mov_b32_e32 v39, v35
.LBB0_550:
	s_lshl_b64 s[2:3], s[28:29], 10
	v_cvt_pk_bf16_f32 v28, v36, v37
	v_cvt_pk_bf16_f32 v29, v38, v39
	v_cvt_pk_bf16_f32 v30, v40, v41
	v_cvt_pk_bf16_f32 v31, v42, v43
	v_lshl_add_u64 v[32:33], v[48:49], 0, s[2:3]
	global_store_dwordx4 v[32:33], v[28:31], off nt
	v_lshlrev_b32_e32 v34, 16, v21
	v_and_b32_e32 v35, 0xffff0000, v21
	v_lshlrev_b32_e32 v30, 16, v20
	v_and_b32_e32 v31, 0xffff0000, v20
	v_pk_mul_f32 v[32:33], v[30:31], v[30:31]
	v_lshl_add_u64 v[28:29], v[50:51], 0, s[2:3]
	v_pk_mul_f32 v[20:21], v[34:35], v[34:35]
	v_add_f32_e32 v32, v32, v33
	global_store_dwordx4 v[28:29], v[24:27], off nt
	v_add_f32_e32 v20, v20, v32
	v_add_f32_e32 v20, v21, v20
	v_lshlrev_b32_e32 v26, 16, v22
	v_and_b32_e32 v27, 0xffff0000, v22
	v_pk_mul_f32 v[24:25], v[26:27], v[26:27]
	v_lshlrev_b32_e32 v22, 16, v23
	v_and_b32_e32 v23, 0xffff0000, v23
	v_add_f32_e32 v20, v24, v20
	v_pk_mul_f32 v[28:29], v[22:23], v[22:23]
	v_add_f32_e32 v20, v25, v20
	v_add_f32_e32 v20, v28, v20
	v_add_f32_e32 v20, v29, v20
	ds_bpermute_b32 v21, v45, v20
	s_ashr_i32 s27, s26, 31
	s_mov_b64 s[28:29], -1
	s_waitcnt lgkmcnt(0)
	v_add_f32_e32 v20, v20, v21
	ds_bpermute_b32 v21, v62, v20
	s_waitcnt lgkmcnt(0)
	v_add_f32_e32 v20, v20, v21
	ds_bpermute_b32 v21, v63, v20
	s_waitcnt lgkmcnt(0)
	v_add_f32_e32 v20, v20, v21
	ds_bpermute_b32 v21, v64, v20
	s_waitcnt lgkmcnt(0)
	v_add_f32_e32 v20, v20, v21
	v_fmamk_f32 v20, v20, 0x3c000000, v221
	v_cmp_gt_f32_e32 vcc, s42, v20
	v_mul_f32_e32 v21, 0x4b800000, v20
	s_nop 0
	v_cndmask_b32_e32 v20, v20, v21, vcc
	v_rsq_f32_e32 v20, v20
	s_nop 0
	v_mul_f32_e32 v21, 0x45800000, v20
	v_cndmask_b32_e32 v28, v20, v21, vcc
	v_pk_mul_f32 v[20:21], v[0:1], v[28:29] op_sel_hi:[1,0]
	v_pk_mul_f32 v[32:33], v[4:5], v[28:29] op_sel_hi:[1,0]
	v_pk_mul_f32 v[24:25], v[20:21], v[30:31]
	v_pk_mul_f32 v[20:21], v[32:33], v[26:27]
	v_pk_mul_f32 v[26:27], v[2:3], v[28:29] op_sel_hi:[1,0]
	v_pk_mul_f32 v[28:29], v[6:7], v[28:29] op_sel_hi:[1,0]
	v_pk_mul_f32 v[26:27], v[26:27], v[34:35]
	v_pk_mul_f32 v[22:23], v[28:29], v[22:23]
	s_and_b64 vcc, exec, s[8:9]
	s_cbranch_vccnz .LBB0_552
	v_mov_b32_e32 v28, s26
	v_mov_b32_e32 v29, s37
	v_cndmask_b32_e64 v28, v28, v29, s[4:5]
	v_lshlrev_b32_e32 v28, 8, v28
	v_and_b32_e32 v176, 0x3f00, v28
	v_lshl_add_u64 v[28:29], v[46:47], 0, v[176:177]
	global_load_dwordx4 v[34:37], v[28:29], off offset:48
	global_load_dwordx4 v[38:41], v[28:29], off offset:32
	global_load_dwordx4 v[30:33], v[28:29], off offset:16
	global_load_dwordx4 v[54:57], v[28:29], off
	ds_bpermute_b32 v42, v63, v24
	ds_bpermute_b32 v43, v63, v25
	s_mov_b64 s[28:29], 0
	s_waitcnt vmcnt(0)
	v_mov_b32_e32 v29, v56
	v_mov_b32_e32 v56, v55
	s_waitcnt lgkmcnt(0)
	v_pk_mul_f32 v[42:43], v[56:57], v[42:43]
	v_mov_b32_e32 v28, v54
	v_cndmask_b32_e64 v43, v43, -v43, s[6:7]
	v_cndmask_b32_e64 v42, v42, -v42, s[6:7]
	v_pk_fma_f32 v[28:29], v[24:25], v[28:29], v[42:43]
	ds_bpermute_b32 v42, v63, v26
	ds_bpermute_b32 v43, v63, v27
	v_mov_b32_e32 v55, v32
	v_mov_b32_e32 v32, v31
	v_mov_b32_e32 v54, v30
	s_waitcnt lgkmcnt(0)
	v_pk_mul_f32 v[30:31], v[32:33], v[42:43]
	ds_bpermute_b32 v32, v63, v20
	ds_bpermute_b32 v33, v63, v21
	v_mov_b32_e32 v42, v38
	v_mov_b32_e32 v43, v40
	v_mov_b32_e32 v40, v39
	ds_bpermute_b32 v38, v63, v22
	ds_bpermute_b32 v39, v63, v23
	s_waitcnt lgkmcnt(2)
	v_pk_mul_f32 v[32:33], v[40:41], v[32:33]
	v_mov_b32_e32 v41, v36
	v_mov_b32_e32 v36, v35
	v_mov_b32_e32 v40, v34
	s_waitcnt lgkmcnt(0)
	v_pk_mul_f32 v[34:35], v[36:37], v[38:39]
	v_cndmask_b32_e64 v31, v31, -v31, s[6:7]
	v_cndmask_b32_e64 v30, v30, -v30, s[6:7]
	v_cndmask_b32_e64 v33, v33, -v33, s[6:7]
	v_cndmask_b32_e64 v32, v32, -v32, s[6:7]
	v_cndmask_b32_e64 v35, v35, -v35, s[6:7]
	v_cndmask_b32_e64 v34, v34, -v34, s[6:7]
	v_pk_fma_f32 v[30:31], v[26:27], v[54:55], v[30:31]
	v_pk_fma_f32 v[32:33], v[20:21], v[42:43], v[32:33]
	v_pk_fma_f32 v[34:35], v[22:23], v[40:41], v[34:35]
.LBB0_552:
	s_andn2_b64 vcc, exec, s[28:29]
	s_cbranch_vccnz .LBB0_554
	s_load_dwordx2 s[2:3], s[20:21], 0xe0
	s_add_i32 s23, s36, 0x400
	s_and_b32 s23, s23, 0x1fc00
	v_or_b32_e32 v52, s23, v65
	s_waitcnt lgkmcnt(0)
	v_lshl_add_u64 v[32:33], v[52:53], 2, s[2:3]
	s_mov_b64 s[2:3], 0x10000000
	v_lshl_add_u64 v[28:29], v[32:33], 0, s[2:3]
	s_brev_b32 s2, 8
	v_add_co_u32_e32 v30, vcc, s2, v32
	s_mov_b64 s[2:3], 0x14000000
	s_nop 0
	v_addc_co_u32_e32 v31, vcc, 0, v33, vcc
	v_lshl_add_u64 v[34:35], v[32:33], 0, s[2:3]
	v_add_co_u32_e32 v32, vcc, 0x14000000, v32
	global_store_dwordx4 v[30:31], v[24:27], off nt
	global_store_dwordx4 v[28:29], v[20:23], off offset:16 nt
	v_lshlrev_b32_e32 v28, 16, v12
	v_and_b32_e32 v29, 0xffff0000, v12
	v_lshlrev_b32_e32 v30, 16, v13
	v_and_b32_e32 v31, 0xffff0000, v13
	v_addc_co_u32_e32 v33, vcc, 0, v33, vcc
	global_store_dwordx4 v[32:33], v[28:31], off nt
	v_mov_b32_e32 v32, v20
	v_mov_b32_e32 v33, v21
	v_lshlrev_b32_e32 v28, 16, v14
	v_and_b32_e32 v29, 0xffff0000, v14
	v_lshlrev_b32_e32 v30, 16, v15
	v_and_b32_e32 v31, 0xffff0000, v15
	global_store_dwordx4 v[34:35], v[28:31], off offset:16 nt
	v_mov_b32_e32 v34, v22
	v_mov_b32_e32 v35, v23
	v_mov_b32_e32 v28, v24
	v_mov_b32_e32 v29, v25
	v_mov_b32_e32 v30, v26
	v_mov_b32_e32 v31, v27
.LBB0_554:
	s_lshl_b64 s[2:3], s[26:27], 10
	v_cvt_pk_bf16_f32 v20, v28, v29
	v_cvt_pk_bf16_f32 v21, v30, v31
	v_cvt_pk_bf16_f32 v22, v32, v33
	v_cvt_pk_bf16_f32 v23, v34, v35
	v_lshl_add_u64 v[24:25], v[48:49], 0, s[2:3]
	global_store_dwordx4 v[24:25], v[20:23], off nt
	v_lshlrev_b32_e32 v26, 16, v17
	v_and_b32_e32 v27, 0xffff0000, v17
	v_lshlrev_b32_e32 v22, 16, v16
	v_and_b32_e32 v23, 0xffff0000, v16
	v_pk_mul_f32 v[24:25], v[22:23], v[22:23]
	v_lshl_add_u64 v[20:21], v[50:51], 0, s[2:3]
	v_pk_mul_f32 v[16:17], v[26:27], v[26:27]
	v_add_f32_e32 v24, v24, v25
	global_store_dwordx4 v[20:21], v[12:15], off nt
	v_add_f32_e32 v16, v16, v24
	v_add_f32_e32 v16, v17, v16
	v_lshlrev_b32_e32 v12, 16, v18
	v_and_b32_e32 v13, 0xffff0000, v18
	v_pk_mul_f32 v[14:15], v[12:13], v[12:13]
	v_lshlrev_b32_e32 v20, 16, v19
	v_and_b32_e32 v21, 0xffff0000, v19
	v_add_f32_e32 v14, v14, v16
	v_pk_mul_f32 v[18:19], v[20:21], v[20:21]
	v_add_f32_e32 v14, v15, v14
	v_add_f32_e32 v14, v18, v14
	v_add_f32_e32 v14, v19, v14
	ds_bpermute_b32 v15, v45, v14
	s_ashr_i32 s25, s24, 31
	s_mov_b64 s[26:27], -1
	s_waitcnt lgkmcnt(0)
	v_add_f32_e32 v14, v14, v15
	ds_bpermute_b32 v15, v62, v14
	s_waitcnt lgkmcnt(0)
	v_add_f32_e32 v14, v14, v15
	ds_bpermute_b32 v15, v63, v14
	s_waitcnt lgkmcnt(0)
	v_add_f32_e32 v14, v14, v15
	ds_bpermute_b32 v15, v64, v14
	s_waitcnt lgkmcnt(0)
	v_add_f32_e32 v14, v14, v15
	v_fmamk_f32 v14, v14, 0x3c000000, v221
	v_cmp_gt_f32_e32 vcc, s42, v14
	v_mul_f32_e32 v15, 0x4b800000, v14
	s_nop 0
	v_cndmask_b32_e32 v14, v14, v15, vcc
	v_rsq_f32_e32 v14, v14
	s_nop 0
	v_mul_f32_e32 v15, 0x45800000, v14
	v_cndmask_b32_e32 v14, v14, v15, vcc
	v_pk_mul_f32 v[18:19], v[4:5], v[14:15] op_sel_hi:[1,0]
	v_pk_mul_f32 v[16:17], v[0:1], v[14:15] op_sel_hi:[1,0]
	v_pk_mul_f32 v[12:13], v[18:19], v[12:13]
	v_pk_mul_f32 v[18:19], v[2:3], v[14:15] op_sel_hi:[1,0]
	v_pk_mul_f32 v[14:15], v[6:7], v[14:15] op_sel_hi:[1,0]
	v_pk_mul_f32 v[16:17], v[16:17], v[22:23]
	v_pk_mul_f32 v[18:19], v[18:19], v[26:27]
	v_pk_mul_f32 v[14:15], v[14:15], v[20:21]
	s_and_b64 vcc, exec, s[8:9]
	s_cbranch_vccnz .LBB0_556
	v_mov_b32_e32 v20, s24
	v_mov_b32_e32 v21, s37
	v_cndmask_b32_e64 v20, v20, v21, s[4:5]
	v_lshlrev_b32_e32 v20, 8, v20
	v_and_b32_e32 v176, 0x3f00, v20
	v_lshl_add_u64 v[20:21], v[46:47], 0, v[176:177]
	global_load_dwordx4 v[26:29], v[20:21], off offset:48
	global_load_dwordx4 v[30:33], v[20:21], off offset:32
	global_load_dwordx4 v[22:25], v[20:21], off offset:16
	global_load_dwordx4 v[34:37], v[20:21], off
	ds_bpermute_b32 v38, v63, v16
	ds_bpermute_b32 v39, v63, v17
	s_mov_b64 s[26:27], 0
	s_waitcnt vmcnt(0)
	v_mov_b32_e32 v21, v36
	v_mov_b32_e32 v36, v35
	v_mov_b32_e32 v20, v34
	s_waitcnt lgkmcnt(0)
	v_pk_mul_f32 v[34:35], v[36:37], v[38:39]
	v_mov_b32_e32 v37, v24
	v_cndmask_b32_e64 v35, v35, -v35, s[6:7]
	v_cndmask_b32_e64 v34, v34, -v34, s[6:7]
	v_pk_fma_f32 v[20:21], v[16:17], v[20:21], v[34:35]
	ds_bpermute_b32 v34, v63, v18
	ds_bpermute_b32 v35, v63, v19
	v_mov_b32_e32 v24, v23
	v_mov_b32_e32 v36, v22
	s_waitcnt lgkmcnt(0)
	v_pk_mul_f32 v[22:23], v[24:25], v[34:35]
	ds_bpermute_b32 v24, v63, v12
	ds_bpermute_b32 v25, v63, v13
	v_mov_b32_e32 v34, v30
	v_mov_b32_e32 v35, v32
	v_mov_b32_e32 v32, v31
	ds_bpermute_b32 v30, v63, v14
	ds_bpermute_b32 v31, v63, v15
	s_waitcnt lgkmcnt(2)
	v_pk_mul_f32 v[24:25], v[32:33], v[24:25]
	v_mov_b32_e32 v33, v28
	v_mov_b32_e32 v28, v27
	v_mov_b32_e32 v32, v26
	s_waitcnt lgkmcnt(0)
	v_pk_mul_f32 v[26:27], v[28:29], v[30:31]
	v_cndmask_b32_e64 v23, v23, -v23, s[6:7]
	v_cndmask_b32_e64 v22, v22, -v22, s[6:7]
	v_cndmask_b32_e64 v25, v25, -v25, s[6:7]
	v_cndmask_b32_e64 v24, v24, -v24, s[6:7]
	v_cndmask_b32_e64 v27, v27, -v27, s[6:7]
	v_cndmask_b32_e64 v26, v26, -v26, s[6:7]
	v_pk_fma_f32 v[22:23], v[18:19], v[36:37], v[22:23]
	v_pk_fma_f32 v[24:25], v[12:13], v[34:35], v[24:25]
	v_pk_fma_f32 v[26:27], v[14:15], v[32:33], v[26:27]
.LBB0_556:
	s_andn2_b64 vcc, exec, s[26:27]
	s_cbranch_vccnz .LBB0_541
	s_load_dwordx2 s[2:3], s[20:21], 0xe0
	s_add_i32 s8, s36, 0x600
	s_and_b32 s8, s8, 0x1fe00
	v_or_b32_e32 v52, s8, v65
	s_waitcnt lgkmcnt(0)
	v_lshl_add_u64 v[24:25], v[52:53], 2, s[2:3]
	s_mov_b64 s[2:3], 0x10000000
	v_lshl_add_u64 v[20:21], v[24:25], 0, s[2:3]
	s_brev_b32 s2, 8
	v_add_co_u32_e32 v22, vcc, s2, v24
	s_mov_b64 s[2:3], 0x14000000
	s_nop 0
	v_addc_co_u32_e32 v23, vcc, 0, v25, vcc
	v_lshl_add_u64 v[26:27], v[24:25], 0, s[2:3]
	v_add_co_u32_e32 v24, vcc, 0x14000000, v24
	global_store_dwordx4 v[22:23], v[16:19], off nt
	global_store_dwordx4 v[20:21], v[12:15], off offset:16 nt
	v_lshlrev_b32_e32 v20, 16, v8
	v_and_b32_e32 v21, 0xffff0000, v8
	v_lshlrev_b32_e32 v22, 16, v9
	v_and_b32_e32 v23, 0xffff0000, v9
	v_addc_co_u32_e32 v25, vcc, 0, v25, vcc
	global_store_dwordx4 v[24:25], v[20:23], off nt
	v_mov_b32_e32 v24, v12
	v_mov_b32_e32 v25, v13
	v_lshlrev_b32_e32 v20, 16, v10
	v_and_b32_e32 v21, 0xffff0000, v10
	v_lshlrev_b32_e32 v22, 16, v11
	v_and_b32_e32 v23, 0xffff0000, v11
	global_store_dwordx4 v[26:27], v[20:23], off offset:16 nt
	v_mov_b32_e32 v26, v14
	v_mov_b32_e32 v27, v15
	v_mov_b32_e32 v20, v16
	v_mov_b32_e32 v21, v17
	v_mov_b32_e32 v22, v18
	v_mov_b32_e32 v23, v19
	s_branch .LBB0_541

.LBB0_985:
	v_add_co_u32_e32 v148, vcc, s25, v144
	v_lshl_add_u64 v[64:65], v[146:147], 0, s[8:9]
	s_nop 0
	v_addc_co_u32_e32 v149, vcc, -1, v145, vcc
	v_add_co_u32_e32 v150, vcc, s26, v144
	v_add_co_u32_e64 v68, s[0:1], s22, v64
	s_nop 0
	v_addc_co_u32_e32 v151, vcc, -1, v145, vcc
	v_add_co_u32_e32 v152, vcc, s27, v144
	v_addc_co_u32_e64 v69, s[0:1], 0, v65, s[0:1]
	s_nop 0
	v_addc_co_u32_e32 v153, vcc, -1, v145, vcc
	v_add_co_u32_e32 v66, vcc, 0x6a600000, v64
	v_add_co_u32_e64 v70, s[0:1], s23, v64
	s_nop 0
	v_addc_co_u32_e32 v67, vcc, 0, v65, vcc
	v_addc_co_u32_e64 v71, s[0:1], 0, v65, s[0:1]
	global_load_dwordx4 v[124:127], v[68:69], off
	global_load_dwordx4 v[120:123], v[70:71], off
	global_load_dwordx4 v[116:119], v[68:69], off offset:1024
	global_load_dwordx4 v[112:115], v[70:71], off offset:1024
	global_load_dwordx4 v[108:111], v[68:69], off offset:2048
	global_load_dwordx4 v[104:107], v[70:71], off offset:2048
	global_load_dwordx4 v[100:103], v[68:69], off offset:3072
	global_load_dwordx4 v[96:99], v[70:71], off offset:3072
	v_add_co_u32_e32 v64, vcc, 0x72600000, v64
	global_load_dwordx4 v[92:95], v[66:67], off
	global_load_dwordx4 v[88:91], v[66:67], off offset:1024
	global_load_dwordx4 v[84:87], v[66:67], off offset:2048
	global_load_dwordx4 v[80:83], v[66:67], off offset:3072
	v_addc_co_u32_e32 v65, vcc, 0, v65, vcc
	global_load_dwordx4 v[76:79], v[64:65], off
	global_load_dwordx4 v[72:75], v[64:65], off offset:1024
	global_load_dwordx4 v[68:71], v[64:65], off offset:2048
	s_nop 0
	global_load_dwordx4 v[64:67], v[64:65], off offset:3072
	s_ashr_i32 s11, s10, 31
	s_lshl_b64 s[0:1], s[10:11], 13
	s_add_u32 s12, s16, s0
	s_addc_u32 s13, s17, s1
	s_add_u32 s0, s18, s0
	v_lshl_add_u64 v[154:155], s[12:13], 0, v[136:137]
	s_addc_u32 s1, s19, s1
	v_lshl_add_u64 v[156:157], s[12:13], 0, v[138:139]
	v_lshl_add_u64 v[168:169], s[0:1], 0, v[136:137]
	v_lshl_add_u64 v[166:167], s[0:1], 0, v[138:139]
	s_lshl_b64 s[12:13], s[10:11], 14
	s_add_u32 s0, s4, s12
	s_addc_u32 s1, s5, s13
	v_lshl_add_u64 v[164:165], s[0:1], 0, v[128:129]
	v_lshl_add_u64 v[162:163], s[0:1], 0, v[130:131]
	v_lshl_add_u64 v[160:161], s[0:1], 0, v[132:133]
	v_lshl_add_u64 v[158:159], s[0:1], 0, v[134:135]
	s_add_i32 s10, s10, 2
	s_add_u32 s8, s8, 0x4000
	s_addc_u32 s9, s9, 0
	s_cmp_eq_u32 s8, 0x10000
	s_waitcnt vmcnt(0)
	v_lshlrev_b32_e32 v178, 16, v124
	v_and_b32_e32 v179, 0xffff0000, v124
	v_lshlrev_b32_e32 v180, 16, v120
	v_and_b32_e32 v181, 0xffff0000, v120
	v_lshlrev_b32_e32 v124, 16, v125
	v_and_b32_e32 v125, 0xffff0000, v125
	v_lshlrev_b32_e32 v120, 16, v121
	v_and_b32_e32 v121, 0xffff0000, v121
	v_lshlrev_b32_e32 v182, 16, v126
	v_and_b32_e32 v183, 0xffff0000, v126
	v_lshlrev_b32_e32 v184, 16, v122
	v_and_b32_e32 v185, 0xffff0000, v122
	v_lshlrev_b32_e32 v126, 16, v127
	v_and_b32_e32 v127, 0xffff0000, v127
	v_lshlrev_b32_e32 v122, 16, v123
	v_and_b32_e32 v123, 0xffff0000, v123
	v_lshlrev_b32_e32 v186, 16, v116
	v_and_b32_e32 v187, 0xffff0000, v116
	v_lshlrev_b32_e32 v188, 16, v112
	v_and_b32_e32 v189, 0xffff0000, v112
	v_lshlrev_b32_e32 v116, 16, v117
	v_and_b32_e32 v117, 0xffff0000, v117
	v_lshlrev_b32_e32 v112, 16, v113
	v_and_b32_e32 v113, 0xffff0000, v113
	v_lshlrev_b32_e32 v190, 16, v118
	v_and_b32_e32 v191, 0xffff0000, v118
	v_lshlrev_b32_e32 v192, 16, v114
	v_and_b32_e32 v193, 0xffff0000, v114
	v_lshlrev_b32_e32 v118, 16, v119
	v_and_b32_e32 v119, 0xffff0000, v119
	v_lshlrev_b32_e32 v114, 16, v115
	v_and_b32_e32 v115, 0xffff0000, v115
	v_lshlrev_b32_e32 v194, 16, v108
	v_and_b32_e32 v195, 0xffff0000, v108
	v_lshlrev_b32_e32 v196, 16, v104
	v_and_b32_e32 v197, 0xffff0000, v104
	v_lshlrev_b32_e32 v108, 16, v109
	v_and_b32_e32 v109, 0xffff0000, v109
	v_lshlrev_b32_e32 v104, 16, v105
	v_and_b32_e32 v105, 0xffff0000, v105
	v_lshlrev_b32_e32 v198, 16, v110
	v_and_b32_e32 v199, 0xffff0000, v110
	v_lshlrev_b32_e32 v200, 16, v106
	v_and_b32_e32 v201, 0xffff0000, v106
	v_lshlrev_b32_e32 v110, 16, v111
	v_and_b32_e32 v111, 0xffff0000, v111
	v_lshlrev_b32_e32 v106, 16, v107
	v_and_b32_e32 v107, 0xffff0000, v107
	v_lshlrev_b32_e32 v202, 16, v100
	v_and_b32_e32 v203, 0xffff0000, v100
	v_lshlrev_b32_e32 v204, 16, v96
	v_and_b32_e32 v205, 0xffff0000, v96
	v_lshlrev_b32_e32 v100, 16, v101
	v_and_b32_e32 v101, 0xffff0000, v101
	v_lshlrev_b32_e32 v96, 16, v97
	v_and_b32_e32 v97, 0xffff0000, v97
	v_lshlrev_b32_e32 v206, 16, v102
	v_and_b32_e32 v207, 0xffff0000, v102
	v_lshlrev_b32_e32 v208, 16, v98
	v_and_b32_e32 v209, 0xffff0000, v98
	v_lshlrev_b32_e32 v102, 16, v103
	v_and_b32_e32 v103, 0xffff0000, v103
	v_lshlrev_b32_e32 v98, 16, v99
	v_and_b32_e32 v99, 0xffff0000, v99
	v_lshlrev_b32_e32 v210, 16, v92
	v_and_b32_e32 v211, 0xffff0000, v92
	v_lshlrev_b32_e32 v92, 16, v93
	v_and_b32_e32 v93, 0xffff0000, v93
	v_lshlrev_b32_e32 v212, 16, v94
	v_and_b32_e32 v213, 0xffff0000, v94
	v_lshlrev_b32_e32 v94, 16, v95
	v_and_b32_e32 v95, 0xffff0000, v95
	v_pk_add_f32 v[178:179], v[178:179], v[180:181]
	v_pk_add_f32 v[120:121], v[124:125], v[120:121]
	v_pk_add_f32 v[122:123], v[126:127], v[122:123]
	v_pk_add_f32 v[126:127], v[186:187], v[188:189]
	v_pk_add_f32 v[112:113], v[116:117], v[112:113]
	v_pk_add_f32 v[116:117], v[190:191], v[192:193]
	v_pk_add_f32 v[114:115], v[118:119], v[114:115]
	v_pk_add_f32 v[104:105], v[108:109], v[104:105]
	v_pk_add_f32 v[108:109], v[198:199], v[200:201]
	v_pk_add_f32 v[106:107], v[110:111], v[106:107]
	v_pk_add_f32 v[110:111], v[202:203], v[204:205]
	v_pk_add_f32 v[96:97], v[100:101], v[96:97]
	v_pk_add_f32 v[98:99], v[102:103], v[98:99]
	v_lshlrev_b32_e32 v102, 16, v76
	v_and_b32_e32 v103, 0xffff0000, v76
	v_lshlrev_b32_e32 v76, 16, v77
	v_and_b32_e32 v77, 0xffff0000, v77
	v_lshlrev_b32_e32 v180, 16, v78
	v_and_b32_e32 v181, 0xffff0000, v78
	v_lshlrev_b32_e32 v78, 16, v79
	v_and_b32_e32 v79, 0xffff0000, v79
	v_lshlrev_b32_e32 v214, 16, v88
	v_and_b32_e32 v215, 0xffff0000, v88
	v_lshlrev_b32_e32 v88, 16, v89
	v_and_b32_e32 v89, 0xffff0000, v89
	v_lshlrev_b32_e32 v216, 16, v90
	v_and_b32_e32 v217, 0xffff0000, v90
	v_lshlrev_b32_e32 v90, 16, v91
	v_and_b32_e32 v91, 0xffff0000, v91
	v_lshlrev_b32_e32 v218, 16, v84
	v_and_b32_e32 v219, 0xffff0000, v84
	v_lshlrev_b32_e32 v84, 16, v85
	v_and_b32_e32 v85, 0xffff0000, v85
	v_lshlrev_b32_e32 v220, 16, v86
	v_and_b32_e32 v221, 0xffff0000, v86
	v_lshlrev_b32_e32 v86, 16, v87
	v_and_b32_e32 v87, 0xffff0000, v87
	v_lshlrev_b32_e32 v222, 16, v80
	v_and_b32_e32 v223, 0xffff0000, v80
	v_lshlrev_b32_e32 v80, 16, v81
	v_and_b32_e32 v81, 0xffff0000, v81
	v_lshlrev_b32_e32 v224, 16, v82
	v_and_b32_e32 v225, 0xffff0000, v82
	v_lshlrev_b32_e32 v82, 16, v83
	v_and_b32_e32 v83, 0xffff0000, v83
	v_pk_add_f32 v[124:125], v[182:183], v[184:185]
	v_pk_add_f32 v[118:119], v[194:195], v[196:197]
	v_pk_add_f32 v[100:101], v[206:207], v[208:209]
	v_lshlrev_b32_e32 v182, 16, v72
	v_and_b32_e32 v183, 0xffff0000, v72
	v_lshlrev_b32_e32 v72, 16, v73
	v_and_b32_e32 v73, 0xffff0000, v73
	v_lshlrev_b32_e32 v184, 16, v74
	v_and_b32_e32 v185, 0xffff0000, v74
	v_lshlrev_b32_e32 v74, 16, v75
	v_and_b32_e32 v75, 0xffff0000, v75
	v_lshlrev_b32_e32 v186, 16, v68
	v_and_b32_e32 v187, 0xffff0000, v68
	v_lshlrev_b32_e32 v68, 16, v69
	v_and_b32_e32 v69, 0xffff0000, v69
	v_lshlrev_b32_e32 v188, 16, v70
	v_and_b32_e32 v189, 0xffff0000, v70
	v_lshlrev_b32_e32 v70, 16, v71
	v_and_b32_e32 v71, 0xffff0000, v71
	v_lshlrev_b32_e32 v190, 16, v64
	v_and_b32_e32 v191, 0xffff0000, v64
	v_lshlrev_b32_e32 v64, 16, v65
	v_and_b32_e32 v65, 0xffff0000, v65
	v_lshlrev_b32_e32 v192, 16, v66
	v_and_b32_e32 v193, 0xffff0000, v66
	v_lshlrev_b32_e32 v66, 16, v67
	v_and_b32_e32 v67, 0xffff0000, v67
	v_mul_f32_e32 v194, v178, v178
	v_mul_f32_e32 v196, v120, v120
	v_mov_b32_e32 v204, v127
	v_mov_b32_e32 v205, v113
	v_mul_f32_e32 v206, v117, v117
	v_mul_f32_e32 v208, v115, v115
	v_mov_b32_e32 v232, v109
	v_mov_b32_e32 v233, v107
	v_mul_f32_e32 v234, v110, v110
	v_mul_f32_e32 v236, v96, v96
	v_pk_add_f32 v[102:103], v[210:211], v[102:103]
	v_pk_add_f32 v[76:77], v[92:93], v[76:77]
	v_pk_add_f32 v[92:93], v[212:213], v[180:181]
	v_pk_add_f32 v[78:79], v[94:95], v[78:79]
	v_pk_mul_f32 v[200:201], v[122:123], v[122:123]
	v_mov_b32_e32 v202, v126
	v_mov_b32_e32 v203, v112
	v_pk_mul_f32 v[226:227], v[118:119], v[118:119]
	v_mov_b32_e32 v230, v108
	v_mov_b32_e32 v231, v106
	v_pk_mul_f32 v[240:241], v[98:99], v[98:99]
	v_pk_add_f32 v[94:95], v[214:215], v[182:183]
	v_pk_add_f32 v[72:73], v[88:89], v[72:73]
	v_pk_add_f32 v[88:89], v[216:217], v[184:185]
	v_pk_add_f32 v[74:75], v[90:91], v[74:75]
	v_pk_add_f32 v[90:91], v[218:219], v[186:187]
	v_pk_add_f32 v[68:69], v[84:85], v[68:69]
	v_pk_add_f32 v[84:85], v[220:221], v[188:189]
	v_pk_add_f32 v[70:71], v[86:87], v[70:71]
	v_pk_add_f32 v[86:87], v[222:223], v[190:191]
	v_pk_add_f32 v[64:65], v[80:81], v[64:65]
	v_pk_add_f32 v[80:81], v[224:225], v[192:193]
	v_pk_add_f32 v[66:67], v[82:83], v[66:67]
	v_pk_fma_f32 v[82:83], v[178:179], v[178:179], v[194:195] op_sel_hi:[1,1,0]
	v_pk_fma_f32 v[180:181], v[120:121], v[120:121], v[196:197] op_sel_hi:[1,1,0]
	v_pk_mul_f32 v[182:183], v[204:205], v[204:205]
	v_pk_fma_f32 v[184:185], v[116:117], v[116:117], v[206:207] op_sel_hi:[1,1,0]
	v_pk_fma_f32 v[186:187], v[114:115], v[114:115], v[208:209] op_sel_hi:[1,1,0]
	v_pk_mul_f32 v[188:189], v[232:233], v[232:233]
	v_pk_fma_f32 v[190:191], v[110:111], v[110:111], v[234:235] op_sel_hi:[1,1,0]
	v_pk_fma_f32 v[192:193], v[96:97], v[96:97], v[236:237] op_sel_hi:[1,1,0]
	v_mov_b32_e32 v196, v103
	v_mov_b32_e32 v197, v77
	v_mov_b32_e32 v206, v93
	v_mov_b32_e32 v207, v79
	v_mov_b32_e32 v194, v102
	v_mov_b32_e32 v195, v76
	v_mov_b32_e32 v204, v92
	v_mov_b32_e32 v205, v78
	v_mov_b32_e32 v82, v200
	v_mov_b32_e32 v180, v201
	v_pk_fma_f32 v[182:183], v[202:203], v[202:203], v[182:183]
	v_mov_b32_e32 v185, v226
	v_mov_b32_e32 v187, v227
	v_pk_fma_f32 v[188:189], v[230:231], v[230:231], v[188:189]
	v_mov_b32_e32 v190, v240
	v_mov_b32_e32 v192, v241
	v_pk_mul_f32 v[196:197], v[196:197], v[196:197]
	v_pk_mul_f32 v[200:201], v[206:207], v[206:207]
	v_mul_f32_e32 v208, v94, v94
	v_mul_f32_e32 v210, v72, v72
	v_pk_add_f32 v[82:83], v[82:83], v[180:181]
	v_pk_add_f32 v[180:181], v[182:183], v[182:183] op_sel:[0,1] op_sel_hi:[1,0]
	v_pk_add_f32 v[182:183], v[184:185], v[186:187]
	v_pk_add_f32 v[184:185], v[188:189], v[188:189] op_sel_hi:[0,1]
	v_pk_add_f32 v[186:187], v[190:191], v[192:193]
	v_pk_fma_f32 v[188:189], v[194:195], v[194:195], v[196:197]
	v_pk_fma_f32 v[190:191], v[204:205], v[204:205], v[200:201]
	v_pk_mul_f32 v[212:213], v[88:89], v[88:89]
	v_pk_mul_f32 v[214:215], v[74:75], v[74:75]
	v_pk_fma_f32 v[202:203], v[94:95], v[94:95], v[208:209] op_sel_hi:[1,1,0]
	v_pk_fma_f32 v[206:207], v[72:73], v[72:73], v[210:211] op_sel_hi:[1,1,0]
	v_pk_add_f32 v[188:189], v[188:189], v[188:189] op_sel_hi:[0,1]
	v_pk_add_f32 v[190:191], v[190:191], v[190:191] op_sel_hi:[0,1]
	v_mov_b32_e32 v218, v91
	v_mov_b32_e32 v219, v69
	v_mov_b32_e32 v202, v214
	v_mov_b32_e32 v206, v215
	v_mov_b32_e32 v188, v212
	v_mov_b32_e32 v190, v213
	v_mov_b32_e32 v216, v90
	v_mov_b32_e32 v217, v68
	v_pk_mul_f32 v[208:209], v[218:219], v[218:219]
	v_pk_add_f32 v[196:197], v[202:203], v[206:207]
	v_pk_add_f32 v[188:189], v[188:189], v[190:191]
	v_mul_f32_e32 v220, v85, v85
	v_mul_f32_e32 v222, v71, v71
	v_pk_fma_f32 v[192:193], v[216:217], v[216:217], v[208:209]
	v_pk_add_f32 v[188:189], v[188:189], v[196:197]
	v_pk_mul_f32 v[224:225], v[86:87], v[86:87]
	v_pk_mul_f32 v[232:233], v[64:65], v[64:65]
	v_pk_fma_f32 v[210:211], v[84:85], v[84:85], v[220:221] op_sel_hi:[1,1,0]
	v_pk_fma_f32 v[218:219], v[70:71], v[70:71], v[222:223] op_sel_hi:[1,1,0]
	v_pk_add_f32 v[192:193], v[192:193], v[192:193] op_sel:[0,1] op_sel_hi:[1,0]
	v_pk_add_f32 v[188:189], v[188:189], v[188:189] op_sel:[0,1] op_sel_hi:[1,0]
	v_mov_b32_e32 v236, v81
	v_mov_b32_e32 v237, v67
	v_mov_b32_e32 v211, v224
	v_mov_b32_e32 v219, v225
	v_mov_b32_e32 v193, v233
	v_mov_b32_e32 v189, v232
	v_mov_b32_e32 v234, v80
	v_mov_b32_e32 v235, v66
	v_pk_mul_f32 v[220:221], v[236:237], v[236:237]
	v_pk_add_f32 v[200:201], v[210:211], v[218:219]
	v_pk_add_f32 v[188:189], v[188:189], v[192:193]
	v_pk_fma_f32 v[194:195], v[234:235], v[234:235], v[220:221]
	v_pk_add_f32 v[188:189], v[200:201], v[188:189]
	v_pk_mul_f32 v[198:199], v[124:125], v[124:125]
	v_pk_add_f32 v[194:195], v[194:195], v[194:195] op_sel_hi:[0,1]
	v_pk_add_f32 v[188:189], v[188:189], v[188:189] op_sel_hi:[0,1]
	v_mov_b32_e32 v194, v198
	v_mov_b32_e32 v188, v199
	v_pk_add_f32 v[188:189], v[194:195], v[188:189]
	v_pk_mul_f32 v[228:229], v[104:105], v[104:105]
	v_pk_add_f32 v[82:83], v[188:189], v[82:83]
	v_mov_b32_e32 v181, v229
	v_pk_add_f32 v[82:83], v[82:83], v[82:83] op_sel:[0,1] op_sel_hi:[1,0]
	v_pk_mul_f32 v[238:239], v[100:101], v[100:101]
	v_mov_b32_e32 v83, v228
	v_pk_add_f32 v[82:83], v[82:83], v[180:181]
	v_mov_b32_e32 v184, v238
	v_pk_add_f32 v[82:83], v[182:183], v[82:83]
	s_nop 0
	v_pk_add_f32 v[82:83], v[82:83], v[82:83] op_sel_hi:[0,1]
	v_mov_b32_e32 v82, v239
	v_pk_add_f32 v[82:83], v[184:185], v[82:83]
	s_nop 0
	v_pk_add_f32 v[82:83], v[82:83], v[186:187]
	s_nop 0
	v_add_f32_e32 v82, v82, v83
	ds_bpermute_b32 v83, v170, v82
	s_waitcnt lgkmcnt(0)
	v_add_f32_e32 v82, v82, v83
	ds_bpermute_b32 v83, v171, v82
	s_waitcnt lgkmcnt(0)
	v_add_f32_e32 v82, v82, v83
	ds_bpermute_b32 v83, v172, v82
	s_waitcnt lgkmcnt(0)
	v_add_f32_e32 v82, v82, v83
	ds_bpermute_b32 v83, v173, v82
	s_waitcnt lgkmcnt(0)
	v_add_f32_e32 v82, v82, v83
	ds_bpermute_b32 v83, v174, v82
	s_waitcnt lgkmcnt(0)
	v_add_f32_e32 v82, v82, v83
	ds_bpermute_b32 v83, v175, v82
	s_waitcnt lgkmcnt(0)
	v_add_f32_e32 v82, v82, v83
	v_fmamk_f32 v82, v82, 0x39800000, v176
	v_mul_f32_e32 v83, 0x4b800000, v82
	v_cmp_gt_f32_e32 vcc, s24, v82
	s_nop 1
	v_cndmask_b32_e32 v82, v82, v83, vcc
	v_rsq_f32_e32 v82, v82
	s_nop 0
	v_mul_f32_e32 v83, 0x45800000, v82
	v_cndmask_b32_e32 v82, v82, v83, vcc
	v_pk_mul_f32 v[102:103], v[102:103], v[82:83] op_sel_hi:[1,0]
	v_pk_mul_f32 v[76:77], v[76:77], v[82:83] op_sel_hi:[1,0]
	v_pk_mul_f32 v[92:93], v[92:93], v[82:83] op_sel_hi:[1,0]
	v_pk_mul_f32 v[78:79], v[78:79], v[82:83] op_sel_hi:[1,0]
	v_pk_mul_f32 v[94:95], v[94:95], v[82:83] op_sel_hi:[1,0]
	v_pk_mul_f32 v[72:73], v[72:73], v[82:83] op_sel_hi:[1,0]
	v_pk_mul_f32 v[88:89], v[88:89], v[82:83] op_sel_hi:[1,0]
	v_pk_mul_f32 v[180:181], v[74:75], v[82:83] op_sel_hi:[1,0]
	v_pk_mul_f32 v[90:91], v[90:91], v[82:83] op_sel_hi:[1,0]
	v_pk_mul_f32 v[182:183], v[68:69], v[82:83] op_sel_hi:[1,0]
	v_pk_mul_f32 v[188:189], v[64:65], v[82:83] op_sel_hi:[1,0]
	v_pk_mul_f32 v[192:193], v[66:67], v[82:83] op_sel_hi:[1,0]
	v_pk_mul_f32 v[66:67], v[6:7], v[76:77]
	v_pk_mul_f32 v[64:65], v[4:5], v[102:103]
	v_pk_mul_f32 v[84:85], v[84:85], v[82:83] op_sel_hi:[1,0]
	v_pk_mul_f32 v[184:185], v[70:71], v[82:83] op_sel_hi:[1,0]
	v_pk_mul_f32 v[186:187], v[86:87], v[82:83] op_sel_hi:[1,0]
	v_pk_mul_f32 v[190:191], v[80:81], v[82:83] op_sel_hi:[1,0]
	v_pk_mul_f32 v[178:179], v[178:179], v[82:83] op_sel_hi:[1,0]
	v_pk_mul_f32 v[120:121], v[120:121], v[82:83] op_sel_hi:[1,0]
	v_pk_mul_f32 v[124:125], v[124:125], v[82:83] op_sel_hi:[1,0]
	v_pk_mul_f32 v[122:123], v[122:123], v[82:83] op_sel_hi:[1,0]
	v_pk_mul_f32 v[126:127], v[126:127], v[82:83] op_sel_hi:[1,0]
	v_pk_mul_f32 v[112:113], v[112:113], v[82:83] op_sel_hi:[1,0]
	v_pk_mul_f32 v[116:117], v[116:117], v[82:83] op_sel_hi:[1,0]
	v_pk_mul_f32 v[114:115], v[114:115], v[82:83] op_sel_hi:[1,0]
	v_pk_mul_f32 v[118:119], v[118:119], v[82:83] op_sel_hi:[1,0]
	v_pk_mul_f32 v[194:195], v[104:105], v[82:83] op_sel_hi:[1,0]
	v_pk_mul_f32 v[196:197], v[108:109], v[82:83] op_sel_hi:[1,0]
	v_pk_mul_f32 v[198:199], v[106:107], v[82:83] op_sel_hi:[1,0]
	v_pk_mul_f32 v[200:201], v[110:111], v[82:83] op_sel_hi:[1,0]
	v_pk_mul_f32 v[202:203], v[96:97], v[82:83] op_sel_hi:[1,0]
	v_pk_mul_f32 v[204:205], v[100:101], v[82:83] op_sel_hi:[1,0]
	v_pk_mul_f32 v[206:207], v[98:99], v[82:83] op_sel_hi:[1,0]
	v_pk_mul_f32 v[70:71], v[2:3], v[78:79]
	v_pk_mul_f32 v[68:69], v[0:1], v[92:93]
	v_pk_mul_f32 v[74:75], v[14:15], v[72:73]
	v_pk_mul_f32 v[72:73], v[12:13], v[94:95]
	v_pk_mul_f32 v[78:79], v[10:11], v[180:181]
	v_pk_mul_f32 v[76:77], v[8:9], v[88:89]
	v_pk_mul_f32 v[82:83], v[22:23], v[182:183]
	v_pk_mul_f32 v[80:81], v[20:21], v[90:91]
	global_store_dwordx4 v[148:149], v[64:67], off offset:-2064 nt
	global_store_dwordx4 v[148:149], v[68:71], off offset:-2048 nt
	global_store_dwordx4 v[148:149], v[72:75], off offset:-16 nt
	global_store_dwordx4 v[150:151], v[76:79], off offset:-4096 nt
	v_pk_mul_f32 v[86:87], v[18:19], v[184:185]
	v_pk_mul_f32 v[84:85], v[16:17], v[84:85]
	v_pk_mul_f32 v[90:91], v[30:31], v[188:189]
	v_pk_mul_f32 v[88:89], v[28:29], v[186:187]
	v_pk_mul_f32 v[94:95], v[26:27], v[192:193]
	v_pk_mul_f32 v[92:93], v[24:25], v[190:191]
	v_pk_mul_f32 v[98:99], v[38:39], v[120:121]
	v_pk_mul_f32 v[96:97], v[36:37], v[178:179]
	global_store_dwordx4 v[150:151], v[80:83], off offset:-2064 nt
	global_store_dwordx4 v[150:151], v[84:87], off offset:-2048 nt
	global_store_dwordx4 v[150:151], v[88:91], off offset:-16 nt
	global_store_dwordx4 v[150:151], v[92:95], off nt
	v_pk_mul_f32 v[102:103], v[34:35], v[122:123]
	v_pk_mul_f32 v[100:101], v[32:33], v[124:125]
	v_pk_mul_f32 v[106:107], v[46:47], v[112:113]
	v_pk_mul_f32 v[104:105], v[44:45], v[126:127]
	v_pk_mul_f32 v[110:111], v[42:43], v[114:115]
	v_pk_mul_f32 v[108:109], v[40:41], v[116:117]
	v_pk_mul_f32 v[114:115], v[54:55], v[194:195]
	v_pk_mul_f32 v[112:113], v[52:53], v[118:119]
	global_store_dwordx4 v[152:153], v[96:99], off offset:-2064 nt
	global_store_dwordx4 v[152:153], v[100:103], off offset:-2048 nt
	global_store_dwordx4 v[152:153], v[104:107], off offset:-16 nt
	global_store_dwordx4 v[144:145], v[108:111], off offset:-4096 nt
	v_pk_mul_f32 v[118:119], v[50:51], v[198:199]
	v_pk_mul_f32 v[116:117], v[48:49], v[196:197]
	v_pk_mul_f32 v[122:123], v[62:63], v[202:203]
	v_pk_mul_f32 v[120:121], v[60:61], v[200:201]
	v_pk_mul_f32 v[126:127], v[58:59], v[206:207]
	v_pk_mul_f32 v[124:125], v[56:57], v[204:205]
	global_store_dwordx4 v[144:145], v[112:115], off offset:-2064 nt
	global_store_dwordx4 v[144:145], v[116:119], off offset:-2048 nt
	global_store_dwordx4 v[144:145], v[120:123], off offset:-16 nt
	global_store_dwordx4 v[144:145], v[124:127], off nt
	global_load_dwordx4 v[64:67], v[154:155], off
	global_load_dwordx4 v[68:71], v[168:169], off
	global_load_dwordx4 v[72:75], v[154:155], off offset:1024
	global_load_dwordx4 v[76:79], v[168:169], off offset:1024
	global_load_dwordx4 v[80:83], v[154:155], off offset:2048
	global_load_dwordx4 v[84:87], v[168:169], off offset:2048
	global_load_dwordx4 v[88:91], v[154:155], off offset:3072
	global_load_dwordx4 v[92:95], v[168:169], off offset:3072
	global_load_dwordx4 v[96:99], v[156:157], off
	global_load_dwordx4 v[100:103], v[166:167], off
	global_load_dwordx4 v[104:107], v[156:157], off offset:1024
	global_load_dwordx4 v[108:111], v[166:167], off offset:1024
	global_load_dwordx4 v[112:115], v[156:157], off offset:2048
	global_load_dwordx4 v[116:119], v[156:157], off offset:3072
	global_load_dwordx4 v[120:123], v[166:167], off offset:2048
	global_load_dwordx4 v[124:127], v[166:167], off offset:3072
	v_lshl_add_u64 v[144:145], v[144:145], 0, s[6:7]
	s_waitcnt vmcnt(15)
	v_lshlrev_b32_e32 v148, 16, v64
	v_and_b32_e32 v149, 0xffff0000, v64
	s_waitcnt vmcnt(14)
	v_lshlrev_b32_e32 v150, 16, v68
	v_and_b32_e32 v151, 0xffff0000, v68
	v_lshlrev_b32_e32 v64, 16, v65
	v_and_b32_e32 v65, 0xffff0000, v65
	v_lshlrev_b32_e32 v68, 16, v69
	v_and_b32_e32 v69, 0xffff0000, v69
	v_lshlrev_b32_e32 v152, 16, v66
	v_and_b32_e32 v153, 0xffff0000, v66
	v_lshlrev_b32_e32 v154, 16, v70
	v_and_b32_e32 v155, 0xffff0000, v70
	v_lshlrev_b32_e32 v66, 16, v67
	v_and_b32_e32 v67, 0xffff0000, v67
	v_lshlrev_b32_e32 v70, 16, v71
	v_and_b32_e32 v71, 0xffff0000, v71
	v_pk_add_f32 v[148:149], v[148:149], v[150:151]
	v_pk_add_f32 v[64:65], v[64:65], v[68:69]
	v_pk_add_f32 v[68:69], v[152:153], v[154:155]
	v_pk_add_f32 v[66:67], v[66:67], v[70:71]
	s_waitcnt vmcnt(13)
	v_lshlrev_b32_e32 v156, 16, v72
	v_and_b32_e32 v157, 0xffff0000, v72
	s_waitcnt vmcnt(12)
	v_lshlrev_b32_e32 v166, 16, v76
	v_and_b32_e32 v167, 0xffff0000, v76
	v_lshlrev_b32_e32 v72, 16, v73
	v_and_b32_e32 v73, 0xffff0000, v73
	v_lshlrev_b32_e32 v76, 16, v77
	v_and_b32_e32 v77, 0xffff0000, v77
	s_waitcnt vmcnt(2)
	v_lshlrev_b32_e32 v224, 16, v118
	v_and_b32_e32 v225, 0xffff0000, v118
	s_waitcnt vmcnt(0)
	v_lshlrev_b32_e32 v226, 16, v126
	v_and_b32_e32 v227, 0xffff0000, v126
	v_lshlrev_b32_e32 v118, 16, v119
	v_and_b32_e32 v119, 0xffff0000, v119
	v_lshlrev_b32_e32 v126, 16, v127
	v_and_b32_e32 v127, 0xffff0000, v127
	v_mov_b32_e32 v150, v149
	v_mov_b32_e32 v151, v65
	v_mov_b32_e32 v154, v69
	v_mov_b32_e32 v155, v67
	v_lshlrev_b32_e32 v168, 16, v74
	v_and_b32_e32 v169, 0xffff0000, v74
	v_lshlrev_b32_e32 v178, 16, v78
	v_and_b32_e32 v179, 0xffff0000, v78
	v_lshlrev_b32_e32 v74, 16, v75
	v_and_b32_e32 v75, 0xffff0000, v75
	v_lshlrev_b32_e32 v78, 16, v79
	v_and_b32_e32 v79, 0xffff0000, v79
	v_pk_add_f32 v[70:71], v[156:157], v[166:167]
	v_pk_add_f32 v[72:73], v[72:73], v[76:77]
	v_pk_add_f32 v[118:119], v[118:119], v[126:127]
	v_mov_b32_e32 v126, v148
	v_mov_b32_e32 v127, v64
	v_mov_b32_e32 v152, v68
	v_mov_b32_e32 v153, v66
	v_pk_mul_f32 v[150:151], v[150:151], v[150:151]
	v_pk_mul_f32 v[154:155], v[154:155], v[154:155]
	v_lshlrev_b32_e32 v180, 16, v80
	v_and_b32_e32 v181, 0xffff0000, v80
	v_lshlrev_b32_e32 v182, 16, v84
	v_and_b32_e32 v183, 0xffff0000, v84
	v_lshlrev_b32_e32 v80, 16, v81
	v_and_b32_e32 v81, 0xffff0000, v81
	v_lshlrev_b32_e32 v84, 16, v85
	v_and_b32_e32 v85, 0xffff0000, v85
	v_pk_add_f32 v[76:77], v[168:169], v[178:179]
	v_pk_add_f32 v[74:75], v[74:75], v[78:79]
	v_mul_f32_e32 v156, v70, v70
	v_mul_f32_e32 v166, v72, v72
	v_pk_fma_f32 v[126:127], v[126:127], v[126:127], v[150:151]
	v_pk_fma_f32 v[150:151], v[152:153], v[152:153], v[154:155]
	v_pk_add_f32 v[78:79], v[180:181], v[182:183]
	v_pk_add_f32 v[80:81], v[80:81], v[84:85]
	v_pk_mul_f32 v[168:169], v[76:77], v[76:77]
	v_pk_mul_f32 v[178:179], v[74:75], v[74:75]
	v_pk_fma_f32 v[156:157], v[70:71], v[70:71], v[156:157] op_sel_hi:[1,1,0]
	v_pk_fma_f32 v[166:167], v[72:73], v[72:73], v[166:167] op_sel_hi:[1,1,0]
	v_pk_add_f32 v[126:127], v[126:127], v[126:127] op_sel_hi:[0,1]
	v_pk_add_f32 v[150:151], v[150:151], v[150:151] op_sel_hi:[0,1]
	v_lshlrev_b32_e32 v184, 16, v82
	v_and_b32_e32 v185, 0xffff0000, v82
	v_lshlrev_b32_e32 v186, 16, v86
	v_and_b32_e32 v187, 0xffff0000, v86
	v_lshlrev_b32_e32 v82, 16, v83
	v_and_b32_e32 v83, 0xffff0000, v83
	v_lshlrev_b32_e32 v86, 16, v87
	v_and_b32_e32 v87, 0xffff0000, v87
	v_mov_b32_e32 v182, v79
	v_mov_b32_e32 v183, v81
	v_mov_b32_e32 v156, v178
	v_mov_b32_e32 v166, v179
	v_mov_b32_e32 v126, v168
	v_mov_b32_e32 v150, v169
	v_lshlrev_b32_e32 v188, 16, v88
	v_and_b32_e32 v189, 0xffff0000, v88
	v_lshlrev_b32_e32 v190, 16, v92
	v_and_b32_e32 v191, 0xffff0000, v92
	v_lshlrev_b32_e32 v88, 16, v89
	v_and_b32_e32 v89, 0xffff0000, v89
	v_lshlrev_b32_e32 v92, 16, v93
	v_and_b32_e32 v93, 0xffff0000, v93
	v_pk_add_f32 v[84:85], v[184:185], v[186:187]
	v_pk_add_f32 v[82:83], v[82:83], v[86:87]
	v_mov_b32_e32 v180, v78
	v_mov_b32_e32 v181, v80
	v_pk_mul_f32 v[182:183], v[182:183], v[182:183]
	v_pk_add_f32 v[156:157], v[156:157], v[166:167]
	v_pk_add_f32 v[126:127], v[126:127], v[150:151]
	v_lshlrev_b32_e32 v192, 16, v90
	v_and_b32_e32 v193, 0xffff0000, v90
	v_lshlrev_b32_e32 v194, 16, v94
	v_and_b32_e32 v195, 0xffff0000, v94
	v_lshlrev_b32_e32 v90, 16, v91
	v_and_b32_e32 v91, 0xffff0000, v91
	v_lshlrev_b32_e32 v94, 16, v95
	v_and_b32_e32 v95, 0xffff0000, v95
	v_pk_add_f32 v[86:87], v[188:189], v[190:191]
	v_pk_add_f32 v[88:89], v[88:89], v[92:93]
	v_mul_f32_e32 v184, v85, v85
	v_mul_f32_e32 v186, v83, v83
	v_pk_fma_f32 v[152:153], v[180:181], v[180:181], v[182:183]
	v_pk_add_f32 v[126:127], v[126:127], v[156:157]
	v_pk_add_f32 v[92:93], v[192:193], v[194:195]
	v_pk_add_f32 v[90:91], v[90:91], v[94:95]
	v_pk_mul_f32 v[188:189], v[86:87], v[86:87]
	v_pk_mul_f32 v[190:191], v[88:89], v[88:89]
	v_pk_fma_f32 v[184:185], v[84:85], v[84:85], v[184:185] op_sel_hi:[1,1,0]
	v_pk_fma_f32 v[186:187], v[82:83], v[82:83], v[186:187] op_sel_hi:[1,1,0]
	v_pk_add_f32 v[152:153], v[152:153], v[152:153] op_sel:[0,1] op_sel_hi:[1,0]
	v_pk_add_f32 v[126:127], v[126:127], v[126:127] op_sel:[0,1] op_sel_hi:[1,0]
	v_lshlrev_b32_e32 v196, 16, v96
	v_and_b32_e32 v197, 0xffff0000, v96
	v_lshlrev_b32_e32 v198, 16, v100
	v_and_b32_e32 v199, 0xffff0000, v100
	v_lshlrev_b32_e32 v96, 16, v97
	v_and_b32_e32 v97, 0xffff0000, v97
	v_lshlrev_b32_e32 v100, 16, v101
	v_and_b32_e32 v101, 0xffff0000, v101
	v_mov_b32_e32 v194, v93
	v_mov_b32_e32 v195, v91
	v_mov_b32_e32 v185, v188
	v_mov_b32_e32 v187, v189
	v_mov_b32_e32 v153, v191
	v_mov_b32_e32 v127, v190
	v_lshlrev_b32_e32 v200, 16, v98
	v_and_b32_e32 v201, 0xffff0000, v98
	v_lshlrev_b32_e32 v202, 16, v102
	v_and_b32_e32 v203, 0xffff0000, v102
	v_lshlrev_b32_e32 v98, 16, v99
	v_and_b32_e32 v99, 0xffff0000, v99
	v_lshlrev_b32_e32 v102, 16, v103
	v_and_b32_e32 v103, 0xffff0000, v103
	v_pk_add_f32 v[94:95], v[196:197], v[198:199]
	v_pk_add_f32 v[96:97], v[96:97], v[100:101]
	v_mov_b32_e32 v192, v92
	v_mov_b32_e32 v193, v90
	v_pk_mul_f32 v[194:195], v[194:195], v[194:195]
	v_pk_add_f32 v[166:167], v[184:185], v[186:187]
	v_pk_add_f32 v[126:127], v[126:127], v[152:153]
	v_lshlrev_b32_e32 v204, 16, v104
	v_and_b32_e32 v205, 0xffff0000, v104
	v_lshlrev_b32_e32 v206, 16, v108
	v_and_b32_e32 v207, 0xffff0000, v108
	v_lshlrev_b32_e32 v104, 16, v105
	v_and_b32_e32 v105, 0xffff0000, v105
	v_lshlrev_b32_e32 v108, 16, v109
	v_and_b32_e32 v109, 0xffff0000, v109
	v_pk_add_f32 v[100:101], v[200:201], v[202:203]
	v_pk_add_f32 v[98:99], v[98:99], v[102:103]
	v_mul_f32_e32 v196, v94, v94
	v_mul_f32_e32 v198, v96, v96
	v_pk_fma_f32 v[154:155], v[192:193], v[192:193], v[194:195]
	v_pk_add_f32 v[126:127], v[166:167], v[126:127]
	v_pk_add_f32 v[102:103], v[204:205], v[206:207]
	v_pk_add_f32 v[104:105], v[104:105], v[108:109]
	v_pk_mul_f32 v[200:201], v[100:101], v[100:101]
	v_pk_mul_f32 v[202:203], v[98:99], v[98:99]
	v_pk_fma_f32 v[196:197], v[94:95], v[94:95], v[196:197] op_sel_hi:[1,1,0]
	v_pk_fma_f32 v[198:199], v[96:97], v[96:97], v[198:199] op_sel_hi:[1,1,0]
	v_pk_add_f32 v[154:155], v[154:155], v[154:155] op_sel_hi:[0,1]
	v_pk_add_f32 v[126:127], v[126:127], v[126:127] op_sel_hi:[0,1]
	v_lshlrev_b32_e32 v208, 16, v106
	v_and_b32_e32 v209, 0xffff0000, v106
	v_lshlrev_b32_e32 v210, 16, v110
	v_and_b32_e32 v211, 0xffff0000, v110
	v_lshlrev_b32_e32 v106, 16, v107
	v_and_b32_e32 v107, 0xffff0000, v107
	v_lshlrev_b32_e32 v110, 16, v111
	v_and_b32_e32 v111, 0xffff0000, v111
	v_mov_b32_e32 v206, v103
	v_mov_b32_e32 v207, v105
	v_mov_b32_e32 v196, v202
	v_mov_b32_e32 v198, v203
	v_mov_b32_e32 v154, v200
	v_mov_b32_e32 v126, v201
	v_lshlrev_b32_e32 v212, 16, v112
	v_and_b32_e32 v213, 0xffff0000, v112
	v_lshlrev_b32_e32 v214, 16, v120
	v_and_b32_e32 v215, 0xffff0000, v120
	v_lshlrev_b32_e32 v112, 16, v113
	v_and_b32_e32 v113, 0xffff0000, v113
	v_lshlrev_b32_e32 v120, 16, v121
	v_and_b32_e32 v121, 0xffff0000, v121
	v_pk_add_f32 v[108:109], v[208:209], v[210:211]
	v_pk_add_f32 v[106:107], v[106:107], v[110:111]
	v_mov_b32_e32 v204, v102
	v_mov_b32_e32 v205, v104
	v_pk_mul_f32 v[206:207], v[206:207], v[206:207]
	v_pk_add_f32 v[182:183], v[196:197], v[198:199]
	v_pk_add_f32 v[126:127], v[154:155], v[126:127]
	v_lshlrev_b32_e32 v216, 16, v114
	v_and_b32_e32 v217, 0xffff0000, v114
	v_lshlrev_b32_e32 v218, 16, v122
	v_and_b32_e32 v219, 0xffff0000, v122
	v_lshlrev_b32_e32 v114, 16, v115
	v_and_b32_e32 v115, 0xffff0000, v115
	v_lshlrev_b32_e32 v122, 16, v123
	v_and_b32_e32 v123, 0xffff0000, v123
	v_pk_add_f32 v[110:111], v[212:213], v[214:215]
	v_pk_add_f32 v[112:113], v[112:113], v[120:121]
	v_mul_f32_e32 v208, v109, v109
	v_mul_f32_e32 v210, v107, v107
	v_pk_fma_f32 v[178:179], v[204:205], v[204:205], v[206:207]
	v_pk_add_f32 v[126:127], v[126:127], v[182:183]
	v_pk_add_f32 v[120:121], v[216:217], v[218:219]
	v_pk_add_f32 v[114:115], v[114:115], v[122:123]
	v_pk_mul_f32 v[212:213], v[110:111], v[110:111]
	v_pk_mul_f32 v[214:215], v[112:113], v[112:113]
	v_pk_fma_f32 v[208:209], v[108:109], v[108:109], v[208:209] op_sel_hi:[1,1,0]
	v_pk_fma_f32 v[210:211], v[106:107], v[106:107], v[210:211] op_sel_hi:[1,1,0]
	v_pk_add_f32 v[178:179], v[178:179], v[178:179] op_sel:[0,1] op_sel_hi:[1,0]
	v_pk_add_f32 v[126:127], v[126:127], v[126:127] op_sel:[0,1] op_sel_hi:[1,0]
	v_lshlrev_b32_e32 v220, 16, v116
	v_and_b32_e32 v221, 0xffff0000, v116
	v_lshlrev_b32_e32 v222, 16, v124
	v_and_b32_e32 v223, 0xffff0000, v124
	v_lshlrev_b32_e32 v116, 16, v117
	v_and_b32_e32 v117, 0xffff0000, v117
	v_lshlrev_b32_e32 v124, 16, v125
	v_and_b32_e32 v125, 0xffff0000, v125
	v_mov_b32_e32 v218, v121
	v_mov_b32_e32 v219, v115
	v_mov_b32_e32 v209, v212
	v_mov_b32_e32 v211, v213
	v_mov_b32_e32 v179, v215
	v_mov_b32_e32 v127, v214
	v_pk_add_f32 v[122:123], v[220:221], v[222:223]
	v_pk_add_f32 v[116:117], v[116:117], v[124:125]
	v_mov_b32_e32 v216, v120
	v_mov_b32_e32 v217, v114
	v_pk_mul_f32 v[218:219], v[218:219], v[218:219]
	v_pk_add_f32 v[184:185], v[208:209], v[210:211]
	v_pk_add_f32 v[126:127], v[126:127], v[178:179]
	v_pk_add_f32 v[124:125], v[224:225], v[226:227]
	v_mul_f32_e32 v220, v122, v122
	v_mul_f32_e32 v222, v116, v116
	v_pk_fma_f32 v[180:181], v[216:217], v[216:217], v[218:219]
	v_pk_add_f32 v[126:127], v[184:185], v[126:127]
	v_pk_mul_f32 v[224:225], v[124:125], v[124:125]
	v_pk_mul_f32 v[226:227], v[118:119], v[118:119]
	v_pk_fma_f32 v[220:221], v[122:123], v[122:123], v[220:221] op_sel_hi:[1,1,0]
	v_pk_fma_f32 v[222:223], v[116:117], v[116:117], v[222:223] op_sel_hi:[1,1,0]
	v_pk_add_f32 v[180:181], v[180:181], v[180:181] op_sel_hi:[0,1]
	v_pk_add_f32 v[126:127], v[126:127], v[126:127] op_sel_hi:[0,1]
	v_mov_b32_e32 v220, v226
	v_mov_b32_e32 v222, v227
	v_mov_b32_e32 v180, v224
	v_mov_b32_e32 v126, v225
	v_pk_add_f32 v[186:187], v[220:221], v[222:223]
	v_pk_add_f32 v[126:127], v[180:181], v[126:127]
	s_nop 0
	v_pk_add_f32 v[126:127], v[126:127], v[186:187]
	s_nop 0
	v_add_f32_e32 v126, v126, v127
	ds_bpermute_b32 v127, v170, v126
	s_waitcnt lgkmcnt(0)
	v_add_f32_e32 v126, v126, v127
	ds_bpermute_b32 v127, v171, v126
	s_waitcnt lgkmcnt(0)
	v_add_f32_e32 v126, v126, v127
	ds_bpermute_b32 v127, v172, v126
	s_waitcnt lgkmcnt(0)
	v_add_f32_e32 v126, v126, v127
	ds_bpermute_b32 v127, v173, v126
	s_waitcnt lgkmcnt(0)
	v_add_f32_e32 v126, v126, v127
	ds_bpermute_b32 v127, v174, v126
	s_waitcnt lgkmcnt(0)
	v_add_f32_e32 v126, v126, v127
	ds_bpermute_b32 v127, v175, v126
	s_waitcnt lgkmcnt(0)
	v_add_f32_e32 v126, v126, v127
	v_fmamk_f32 v126, v126, 0x39800000, v176
	v_mul_f32_e32 v127, 0x4b800000, v126
	v_cmp_gt_f32_e32 vcc, s24, v126
	s_nop 1
	v_cndmask_b32_e32 v126, v126, v127, vcc
	v_rsq_f32_e32 v126, v126
	s_nop 0
	v_mul_f32_e32 v127, 0x45800000, v126
	v_cndmask_b32_e32 v126, v126, v127, vcc
	v_pk_mul_f32 v[148:149], v[148:149], v[126:127] op_sel_hi:[1,0]
	v_pk_mul_f32 v[64:65], v[64:65], v[126:127] op_sel_hi:[1,0]
	v_pk_mul_f32 v[68:69], v[68:69], v[126:127] op_sel_hi:[1,0]
	v_pk_mul_f32 v[150:151], v[66:67], v[126:127] op_sel_hi:[1,0]
	v_pk_mul_f32 v[152:153], v[70:71], v[126:127] op_sel_hi:[1,0]
	v_pk_mul_f32 v[72:73], v[72:73], v[126:127] op_sel_hi:[1,0]
	v_pk_mul_f32 v[76:77], v[76:77], v[126:127] op_sel_hi:[1,0]
	v_pk_mul_f32 v[154:155], v[74:75], v[126:127] op_sel_hi:[1,0]
	v_pk_mul_f32 v[156:157], v[78:79], v[126:127] op_sel_hi:[1,0]
	v_pk_mul_f32 v[80:81], v[80:81], v[126:127] op_sel_hi:[1,0]
	v_pk_mul_f32 v[66:67], v[6:7], v[64:65]
	v_pk_mul_f32 v[64:65], v[4:5], v[148:149]
	v_pk_mul_f32 v[84:85], v[84:85], v[126:127] op_sel_hi:[1,0]
	v_pk_mul_f32 v[166:167], v[82:83], v[126:127] op_sel_hi:[1,0]
	v_pk_mul_f32 v[168:169], v[86:87], v[126:127] op_sel_hi:[1,0]
	v_pk_mul_f32 v[88:89], v[88:89], v[126:127] op_sel_hi:[1,0]
	v_pk_mul_f32 v[92:93], v[92:93], v[126:127] op_sel_hi:[1,0]
	v_pk_mul_f32 v[178:179], v[90:91], v[126:127] op_sel_hi:[1,0]
	v_pk_mul_f32 v[180:181], v[94:95], v[126:127] op_sel_hi:[1,0]
	v_pk_mul_f32 v[96:97], v[96:97], v[126:127] op_sel_hi:[1,0]
	v_pk_mul_f32 v[70:71], v[2:3], v[150:151]
	v_pk_mul_f32 v[68:69], v[0:1], v[68:69]
	v_pk_mul_f32 v[74:75], v[14:15], v[72:73]
	v_pk_mul_f32 v[72:73], v[12:13], v[152:153]
	v_pk_mul_f32 v[78:79], v[10:11], v[154:155]
	v_pk_mul_f32 v[76:77], v[8:9], v[76:77]
	v_pk_mul_f32 v[82:83], v[22:23], v[80:81]
	v_pk_mul_f32 v[80:81], v[20:21], v[156:157]
	global_store_dwordx4 v[164:165], v[64:67], off nt
	global_store_dwordx4 v[164:165], v[68:71], off offset:16 nt
	global_store_dwordx4 v[164:165], v[72:75], off offset:2048 nt
	global_store_dwordx4 v[164:165], v[76:79], off offset:2064 nt
	v_pk_mul_f32 v[100:101], v[100:101], v[126:127] op_sel_hi:[1,0]
	v_pk_mul_f32 v[182:183], v[98:99], v[126:127] op_sel_hi:[1,0]
	v_pk_mul_f32 v[184:185], v[102:103], v[126:127] op_sel_hi:[1,0]
	v_pk_mul_f32 v[104:105], v[104:105], v[126:127] op_sel_hi:[1,0]
	v_pk_mul_f32 v[108:109], v[108:109], v[126:127] op_sel_hi:[1,0]
	v_pk_mul_f32 v[186:187], v[106:107], v[126:127] op_sel_hi:[1,0]
	v_pk_mul_f32 v[188:189], v[110:111], v[126:127] op_sel_hi:[1,0]
	v_pk_mul_f32 v[112:113], v[112:113], v[126:127] op_sel_hi:[1,0]
	v_pk_mul_f32 v[86:87], v[18:19], v[166:167]
	v_pk_mul_f32 v[84:85], v[16:17], v[84:85]
	v_pk_mul_f32 v[90:91], v[30:31], v[88:89]
	v_pk_mul_f32 v[88:89], v[28:29], v[168:169]
	v_pk_mul_f32 v[94:95], v[26:27], v[178:179]
	v_pk_mul_f32 v[92:93], v[24:25], v[92:93]
	v_pk_mul_f32 v[98:99], v[38:39], v[96:97]
	v_pk_mul_f32 v[96:97], v[36:37], v[180:181]
	global_store_dwordx4 v[162:163], v[80:83], off nt
	global_store_dwordx4 v[162:163], v[84:87], off offset:16 nt
	global_store_dwordx4 v[162:163], v[88:91], off offset:2048 nt
	global_store_dwordx4 v[162:163], v[92:95], off offset:2064 nt
	v_pk_mul_f32 v[120:121], v[120:121], v[126:127] op_sel_hi:[1,0]
	v_pk_mul_f32 v[190:191], v[114:115], v[126:127] op_sel_hi:[1,0]
	v_pk_mul_f32 v[192:193], v[122:123], v[126:127] op_sel_hi:[1,0]
	v_pk_mul_f32 v[122:123], v[116:117], v[126:127] op_sel_hi:[1,0]
	v_pk_mul_f32 v[124:125], v[124:125], v[126:127] op_sel_hi:[1,0]
	v_pk_mul_f32 v[126:127], v[118:119], v[126:127] op_sel_hi:[1,0]
	v_pk_mul_f32 v[102:103], v[34:35], v[182:183]
	v_pk_mul_f32 v[100:101], v[32:33], v[100:101]
	v_pk_mul_f32 v[106:107], v[46:47], v[104:105]
	v_pk_mul_f32 v[104:105], v[44:45], v[184:185]
	v_pk_mul_f32 v[110:111], v[42:43], v[186:187]
	v_pk_mul_f32 v[108:109], v[40:41], v[108:109]
	v_pk_mul_f32 v[114:115], v[54:55], v[112:113]
	v_pk_mul_f32 v[112:113], v[52:53], v[188:189]
	global_store_dwordx4 v[160:161], v[96:99], off nt
	global_store_dwordx4 v[160:161], v[100:103], off offset:16 nt
	global_store_dwordx4 v[160:161], v[104:107], off offset:2048 nt
	global_store_dwordx4 v[160:161], v[108:111], off offset:2064 nt
	v_pk_mul_f32 v[118:119], v[50:51], v[190:191]
	v_pk_mul_f32 v[116:117], v[48:49], v[120:121]
	v_pk_mul_f32 v[122:123], v[62:63], v[122:123]
	v_pk_mul_f32 v[120:121], v[60:61], v[192:193]
	v_pk_mul_f32 v[126:127], v[58:59], v[126:127]
	v_pk_mul_f32 v[124:125], v[56:57], v[124:125]
	global_store_dwordx4 v[158:159], v[112:115], off nt
	global_store_dwordx4 v[158:159], v[116:119], off offset:16 nt
	global_store_dwordx4 v[158:159], v[120:123], off offset:2048 nt
	global_store_dwordx4 v[158:159], v[124:127], off offset:2064 nt
	s_cbranch_scc0 .LBB0_985
	s_add_i32 s14, s14, s15
	s_add_i32 s20, s20, s21
	s_add_i32 s2, s2, s21
	s_cmpk_gt_i32 s14, 0x7ff
	s_cbranch_scc0 .LBB0_984
